# ML_Z GEMM epilogue: operands loaded two row-groups ahead with counted vmcnt; LRU_CONV two rows per item
# speedup vs baseline: 1.2002x; 1.0282x over previous
; #define PG8_STAGE(bufoff, gbase, voff) do { _Pragma("unroll") for (int _i = 0; _i < 2; ++_i) \
;     __builtin_amdgcn_global_load_lds((const unsigned*)((const char*)(gbase) + (voff)[_i]), (PG8_LAS unsigned*)(lds + (bufoff) + ldsw + _i * 8192), 16, 0, 0); } while (0)
; #define PG8_LDA(dst, b, h) do { _Pragma("unroll") for (int m = 0; m < 4; ++m) _Pragma("unroll") for (int k = 0; k < 2; ++k) dst[m][k] = *(const PG8_LAS bf16x8*)(lds + PG8_SA(b, h) + aoff + m * 2048 + k * 1024); } while (0)
; #define PG8_LDB(dst, b, h) do { _Pragma("unroll") for (int n = 0; n < 2; ++n) _Pragma("unroll") for (int k = 0; k < 2; ++k) dst[n][k] = *(const PG8_LAS bf16x8*)(lds + PG8_SB(b, h) + boff + n * 2048 + k * 1024); } while (0)
; #define PG8_MMA(ai, bj, At, Bt) do { __builtin_amdgcn_s_setprio(1); _Pragma("unroll") for (int m = 0; m < 4; ++m) _Pragma("unroll") for (int n = 0; n < 2; ++n) _Pragma("unroll") for (int k = 0; k < 2; ++k) \
;     acc[ai][bj][m][n] = __builtin_amdgcn_mfma_f32_16x16x32_bf16(Bt[n][k], At[m][k], acc[ai][bj][m][n], 0, 0, 0); __builtin_amdgcn_s_setprio(0); } while (0)
; #define PG8_WAIT_L(n) asm volatile("s_waitcnt lgkmcnt(" #n ")" ::: "memory")
; #define PG8_BAR __builtin_amdgcn_s_barrier()
; #define PG8_SCHED __builtin_amdgcn_sched_barrier(0)
; template <class Epi>
; __device__ __forceinline__ void gemm_phase(PG8_LAS unsigned char* lds, const Gemm g, const StaticOrder& S, const Epi& E) {
;     ...
;     for (int t = 0; t < nt; t += 2) {
;       const bool last = (t == nt - 2);
;       const char* a1 = cA + (size_t)(t + 1) * kstep;
;       const char* a2 = last ? nA : cA + (size_t)(t + 2) * kstep; const char* b2 = last ? nB : cB + (size_t)(t + 2) * kstep;
;       const char* a3 = a2 + kstep; const char* b3 = b2 + kstep;
;       PG8_LDB(B0, 0, 0); PG8_SCHED; PG8_LDA(At, 0, 0); PG8_STAGE(PG8_SA(1, 1), a1 + hstep, voffA);
;       PG8_WAIT_L(8); PG8_BAR; PG8_WAIT_L(0); PG8_MMA(0, 0, At, B0); PG8_BAR; PG8_SCHED;
;       PG8_LDB(B1, 0, 1); PG8_STAGE(PG8_SB(0, 0), b2, voffB);
;       PG8_BAR; PG8_WAIT_L(0); PG8_MMA(0, 1, At, B1); PG8_BAR;
;       PG8_LDA(At, 0, 1); PG8_STAGE(PG8_SA(0, 0), a2, voffA);
;       PG8_BAR; PG8_WAIT_L(0); PG8_MMA(1, 0, At, B0); PG8_BAR; PG8_SCHED;
;       PG8_STAGE(PG8_SB(0, 1), b2 + hstep, voffB);
.LBB0_1123:
	s_add_u32 s10, s8, 0xfffc0080
	s_addc_u32 s11, s9, -1
	s_add_i32 s64, 0, 0x10000
	v_add_u32_e32 v162, s64, v164
	ds_read_b128 v[154:157], v162
	ds_read_b128 v[158:161], v162 offset:1024
	ds_read_b128 v[188:191], v162 offset:2048
	ds_read_b128 v[192:195], v162 offset:3072
	s_cmp_eq_u32 s63, 12
	s_cselect_b32 s51, s45, s11
	s_cselect_b32 s50, s59, s10
	s_cselect_b32 s11, s43, s62
	s_cselect_b32 s10, s60, s61
	v_lshl_add_u64 v[162:163], s[8:9], 0, v[150:151]
	s_add_i32 m0, s52, 0xc000
	ds_read_b128 v[196:199], v166
	ds_read_b128 v[200:203], v166 offset:1024
	ds_read_b128 v[204:207], v166 offset:2048
	ds_read_b128 v[208:211], v166 offset:3072
	ds_read_b128 v[212:215], v166 offset:4096
	ds_read_b128 v[216:219], v166 offset:5120
	ds_read_b128 v[220:223], v166 offset:6144
	ds_read_b128 v[224:227], v166 offset:7168
	global_load_lds_dwordx4 v[162:163], off
	v_lshl_add_u64 v[162:163], s[8:9], 0, v[152:153]
	s_add_i32 m0, s52, 0xe000
	s_nop 0
	global_load_lds_dwordx4 v[162:163], off
	s_waitcnt lgkmcnt(8)
	s_barrier
	s_waitcnt lgkmcnt(0)
	s_setprio 1
	s_waitcnt lgkmcnt(0)
	v_mfma_f32_16x16x32_bf16 v[126:129], v[154:157], v[196:199], v[126:129]
	v_mfma_f32_16x16x32_bf16 v[122:125], v[188:191], v[196:199], v[122:125]
	v_mfma_f32_16x16x32_bf16 v[110:113], v[154:157], v[204:207], v[110:113]
	v_mfma_f32_16x16x32_bf16 v[106:109], v[188:191], v[204:207], v[106:109]
	v_mfma_f32_16x16x32_bf16 v[94:97], v[154:157], v[212:215], v[94:97]
	v_mfma_f32_16x16x32_bf16 v[90:93], v[188:191], v[212:215], v[90:93]
	v_mfma_f32_16x16x32_bf16 v[78:81], v[154:157], v[220:223], v[78:81]
	v_mfma_f32_16x16x32_bf16 v[74:77], v[188:191], v[220:223], v[74:77]
	v_mfma_f32_16x16x32_bf16 v[126:129], v[158:161], v[200:203], v[126:129]
	v_mfma_f32_16x16x32_bf16 v[122:125], v[192:195], v[200:203], v[122:125]
	v_mfma_f32_16x16x32_bf16 v[110:113], v[158:161], v[208:211], v[110:113]
	v_mfma_f32_16x16x32_bf16 v[106:109], v[192:195], v[208:211], v[106:109]
	v_mfma_f32_16x16x32_bf16 v[94:97], v[158:161], v[216:219], v[94:97]
	v_mfma_f32_16x16x32_bf16 v[90:93], v[192:195], v[216:219], v[90:93]
	v_mfma_f32_16x16x32_bf16 v[78:81], v[158:161], v[224:227], v[78:81]
	v_mfma_f32_16x16x32_bf16 v[74:77], v[192:195], v[224:227], v[74:77]
	s_setprio 0
	s_barrier
	s_add_i32 s66, 0, 0x14000
	v_add_u32_e32 v162, s66, v164
	s_add_i32 s64, s64, s28
	ds_read_b128 v[228:231], v162
	ds_read_b128 v[232:235], v162 offset:1024
	ds_read_b128 v[236:239], v162 offset:2048
	ds_read_b128 v[240:243], v162 offset:3072
	v_lshl_add_u64 v[162:163], s[10:11], 0, v[0:1]
	s_mov_b32 m0, s64
	v_lshl_add_u64 v[178:179], s[10:11], 0, v[148:149]
	global_load_lds_dwordx4 v[162:163], off
	s_add_i32 m0, s64, 0x2000
	s_nop 0
	global_load_lds_dwordx4 v[178:179], off
	s_barrier
	s_waitcnt lgkmcnt(0)
	s_setprio 1
	s_waitcnt lgkmcnt(0)
	v_mfma_f32_16x16x32_bf16 v[118:121], v[228:231], v[196:199], v[118:121]
	v_mfma_f32_16x16x32_bf16 v[114:117], v[236:239], v[196:199], v[114:117]
	v_mfma_f32_16x16x32_bf16 v[102:105], v[228:231], v[204:207], v[102:105]
	v_mfma_f32_16x16x32_bf16 v[98:101], v[236:239], v[204:207], v[98:101]
	v_mfma_f32_16x16x32_bf16 v[86:89], v[228:231], v[212:215], v[86:89]
	v_mfma_f32_16x16x32_bf16 v[82:85], v[236:239], v[212:215], v[82:85]
	v_mfma_f32_16x16x32_bf16 v[70:73], v[228:231], v[220:223], v[70:73]
	v_mfma_f32_16x16x32_bf16 v[66:69], v[236:239], v[220:223], v[66:69]
	v_mfma_f32_16x16x32_bf16 v[118:121], v[232:235], v[200:203], v[118:121]
	v_mfma_f32_16x16x32_bf16 v[114:117], v[240:243], v[200:203], v[114:117]
	v_mfma_f32_16x16x32_bf16 v[102:105], v[232:235], v[208:211], v[102:105]
	v_mfma_f32_16x16x32_bf16 v[98:101], v[240:243], v[208:211], v[98:101]
	v_mfma_f32_16x16x32_bf16 v[86:89], v[232:235], v[216:219], v[86:89]
	v_mfma_f32_16x16x32_bf16 v[82:85], v[240:243], v[216:219], v[82:85]
	v_mfma_f32_16x16x32_bf16 v[70:73], v[232:235], v[224:227], v[70:73]
	v_mfma_f32_16x16x32_bf16 v[66:69], v[240:243], v[224:227], v[66:69]
	s_setprio 0
	s_mov_b32 m0, s52
	v_lshl_add_u64 v[244:245], s[50:51], 0, v[0:1]
	s_barrier
	ds_read_b128 v[196:199], v166 offset:16384
	ds_read_b128 v[200:203], v166 offset:17408
	ds_read_b128 v[204:207], v166 offset:18432
	ds_read_b128 v[208:211], v166 offset:19456
	ds_read_b128 v[212:215], v166 offset:20480
	ds_read_b128 v[216:219], v166 offset:21504
	ds_read_b128 v[220:223], v166 offset:22528
	ds_read_b128 v[224:227], v166 offset:23552
	global_load_lds_dwordx4 v[244:245], off
	v_lshl_add_u64 v[246:247], s[50:51], 0, v[148:149]
	s_mov_b32 m0, s53
	s_nop 0
	global_load_lds_dwordx4 v[246:247], off
	s_barrier
	s_waitcnt lgkmcnt(0)
	s_setprio 1
	s_waitcnt lgkmcnt(0)
	v_mfma_f32_16x16x32_bf16 v[62:65], v[154:157], v[196:199], v[62:65]
	v_mfma_f32_16x16x32_bf16 v[58:61], v[188:191], v[196:199], v[58:61]
	v_mfma_f32_16x16x32_bf16 v[46:49], v[154:157], v[204:207], v[46:49]
	v_mfma_f32_16x16x32_bf16 v[42:45], v[188:191], v[204:207], v[42:45]
	v_mfma_f32_16x16x32_bf16 v[30:33], v[154:157], v[212:215], v[30:33]
	v_mfma_f32_16x16x32_bf16 v[26:29], v[188:191], v[212:215], v[26:29]
	v_mfma_f32_16x16x32_bf16 v[14:17], v[154:157], v[220:223], v[14:17]
	v_mfma_f32_16x16x32_bf16 v[10:13], v[188:191], v[220:223], v[10:13]
	v_mfma_f32_16x16x32_bf16 v[62:65], v[158:161], v[200:203], v[62:65]
	v_mfma_f32_16x16x32_bf16 v[58:61], v[192:195], v[200:203], v[58:61]
	v_mfma_f32_16x16x32_bf16 v[46:49], v[158:161], v[208:211], v[46:49]
	v_mfma_f32_16x16x32_bf16 v[42:45], v[192:195], v[208:211], v[42:45]
	v_mfma_f32_16x16x32_bf16 v[30:33], v[158:161], v[216:219], v[30:33]
	v_mfma_f32_16x16x32_bf16 v[26:29], v[192:195], v[216:219], v[26:29]
	v_mfma_f32_16x16x32_bf16 v[14:17], v[158:161], v[224:227], v[14:17]
	v_mfma_f32_16x16x32_bf16 v[10:13], v[192:195], v[224:227], v[10:13]
	s_setprio 0
	s_barrier
; #define PG8_STAGE(bufoff, gbase, voff) do { _Pragma("unroll") for (int _i = 0; _i < 2; ++_i) \
;     __builtin_amdgcn_global_load_lds((const unsigned*)((const char*)(gbase) + (voff)[_i]), (PG8_LAS unsigned*)(lds + (bufoff) + ldsw + _i * 8192), 16, 0, 0); } while (0)
; #define PG8_LDA(dst, b, h) do { _Pragma("unroll") for (int m = 0; m < 4; ++m) _Pragma("unroll") for (int k = 0; k < 2; ++k) dst[m][k] = *(const PG8_LAS bf16x8*)(lds + PG8_SA(b, h) + aoff + m * 2048 + k * 1024); } while (0)
; #define PG8_LDB(dst, b, h) do { _Pragma("unroll") for (int n = 0; n < 2; ++n) _Pragma("unroll") for (int k = 0; k < 2; ++k) dst[n][k] = *(const PG8_LAS bf16x8*)(lds + PG8_SB(b, h) + boff + n * 2048 + k * 1024); } while (0)
; #define PG8_MMA(ai, bj, At, Bt) do { __builtin_amdgcn_s_setprio(1); _Pragma("unroll") for (int m = 0; m < 4; ++m) _Pragma("unroll") for (int n = 0; n < 2; ++n) _Pragma("unroll") for (int k = 0; k < 2; ++k) \
;     acc[ai][bj][m][n] = __builtin_amdgcn_mfma_f32_16x16x32_bf16(Bt[n][k], At[m][k], acc[ai][bj][m][n], 0, 0, 0); __builtin_amdgcn_s_setprio(0); } while (0)
; #define PG8_WAIT_V(n) asm volatile("s_waitcnt vmcnt(" #n ")" ::: "memory")
; #define PG8_WAIT_L(n) asm volatile("s_waitcnt lgkmcnt(" #n ")" ::: "memory")
; #define PG8_BAR __builtin_amdgcn_s_barrier()
; #define PG8_SCHED __builtin_amdgcn_sched_barrier(0)
; template <class Epi>
; __device__ __forceinline__ void gemm_phase(PG8_LAS unsigned char* lds, const Gemm g, const StaticOrder& S, const Epi& E) {
;     ...
;       PG8_STAGE(PG8_SB(0, 1), b2 + hstep, voffB);
;       PG8_WAIT_V(6); PG8_BAR; PG8_MMA(1, 1, At, B1); PG8_BAR;
;       PG8_LDB(B0, 1, 0); PG8_SCHED; PG8_LDA(At, 1, 0); PG8_STAGE(PG8_SA(0, 1), a2 + hstep, voffA);
;       PG8_WAIT_L(8); PG8_BAR; PG8_WAIT_L(0); PG8_MMA(0, 0, At, B0); PG8_BAR; PG8_SCHED;
;       PG8_LDB(B1, 1, 1); PG8_STAGE(PG8_SB(1, 0), b3, voffB);
;       PG8_BAR; PG8_WAIT_L(0); PG8_MMA(0, 1, At, B1); PG8_BAR;
;       PG8_LDA(At, 1, 1); PG8_STAGE(PG8_SA(1, 0), a3, voffA);
;       PG8_BAR; PG8_WAIT_L(0); PG8_MMA(1, 0, At, B0); PG8_BAR; PG8_SCHED;
;       PG8_STAGE(PG8_SB(1, 1), b3 + hstep, voffB);
	s_add_u32 s64, s10, 0x40000
	s_addc_u32 s65, s11, 0
	s_add_i32 s66, s66, s28
	v_lshl_add_u64 v[154:155], s[64:65], 0, v[0:1]
	s_mov_b32 m0, s66
	s_nop 0
	global_load_lds_dwordx4 v[154:155], off
	v_lshl_add_u64 v[154:155], s[64:65], 0, v[148:149]
	s_add_i32 m0, s66, 0x2000
	s_nop 0
	global_load_lds_dwordx4 v[154:155], off
	s_waitcnt vmcnt(6)
	s_barrier
	s_setprio 1
	v_mfma_f32_16x16x32_bf16 v[54:57], v[228:231], v[196:199], v[54:57]
	v_mfma_f32_16x16x32_bf16 v[50:53], v[236:239], v[196:199], v[50:53]
	v_mfma_f32_16x16x32_bf16 v[38:41], v[228:231], v[204:207], v[38:41]
	v_mfma_f32_16x16x32_bf16 v[34:37], v[236:239], v[204:207], v[34:37]
	v_mfma_f32_16x16x32_bf16 v[22:25], v[228:231], v[212:215], v[22:25]
	v_mfma_f32_16x16x32_bf16 v[18:21], v[236:239], v[212:215], v[18:21]
	v_mfma_f32_16x16x32_bf16 v[6:9], v[228:231], v[220:223], v[6:9]
	v_mfma_f32_16x16x32_bf16 v[2:5], v[236:239], v[220:223], v[2:5]
	v_mfma_f32_16x16x32_bf16 v[54:57], v[232:235], v[200:203], v[54:57]
	v_mfma_f32_16x16x32_bf16 v[50:53], v[240:243], v[200:203], v[50:53]
	v_mfma_f32_16x16x32_bf16 v[38:41], v[232:235], v[208:211], v[38:41]
	v_mfma_f32_16x16x32_bf16 v[34:37], v[240:243], v[208:211], v[34:37]
	v_mfma_f32_16x16x32_bf16 v[22:25], v[232:235], v[216:219], v[22:25]
	v_mfma_f32_16x16x32_bf16 v[18:21], v[240:243], v[216:219], v[18:21]
	v_mfma_f32_16x16x32_bf16 v[6:9], v[232:235], v[224:227], v[6:9]
	v_mfma_f32_16x16x32_bf16 v[2:5], v[240:243], v[224:227], v[2:5]
	s_setprio 0
	s_add_i32 s64, 0, 0x18000
	v_add_u32_e32 v167, s64, v164
	s_barrier
	ds_read_b128 v[154:157], v167
	ds_read_b128 v[158:161], v167 offset:1024
	ds_read_b128 v[188:191], v167 offset:2048
	ds_read_b128 v[192:195], v167 offset:3072
	s_add_u32 s50, s50, 0x40000
	s_addc_u32 s51, s51, 0
	s_mov_b32 m0, s54
	v_lshl_add_u64 v[228:229], s[50:51], 0, v[0:1]
	ds_read_b128 v[196:199], v166 offset:32768
	ds_read_b128 v[200:203], v166 offset:33792
	ds_read_b128 v[204:207], v166 offset:34816
	ds_read_b128 v[208:211], v166 offset:35840
	ds_read_b128 v[212:215], v166 offset:36864
	ds_read_b128 v[216:219], v166 offset:37888
	ds_read_b128 v[220:223], v166 offset:38912
	ds_read_b128 v[224:227], v166 offset:39936
	global_load_lds_dwordx4 v[228:229], off
	v_lshl_add_u64 v[228:229], s[50:51], 0, v[148:149]
	s_mov_b32 m0, s55
	s_nop 0
	global_load_lds_dwordx4 v[228:229], off
	s_waitcnt lgkmcnt(8)
	s_barrier
	s_waitcnt lgkmcnt(0)
	s_setprio 1
	s_waitcnt lgkmcnt(0)
	v_mfma_f32_16x16x32_bf16 v[126:129], v[154:157], v[196:199], v[126:129]
	v_mfma_f32_16x16x32_bf16 v[122:125], v[188:191], v[196:199], v[122:125]
	v_mfma_f32_16x16x32_bf16 v[110:113], v[154:157], v[204:207], v[110:113]
	v_mfma_f32_16x16x32_bf16 v[106:109], v[188:191], v[204:207], v[106:109]
	v_mfma_f32_16x16x32_bf16 v[94:97], v[154:157], v[212:215], v[94:97]
	v_mfma_f32_16x16x32_bf16 v[90:93], v[188:191], v[212:215], v[90:93]
	v_mfma_f32_16x16x32_bf16 v[78:81], v[154:157], v[220:223], v[78:81]
	v_mfma_f32_16x16x32_bf16 v[74:77], v[188:191], v[220:223], v[74:77]
	v_mfma_f32_16x16x32_bf16 v[126:129], v[158:161], v[200:203], v[126:129]
	v_mfma_f32_16x16x32_bf16 v[122:125], v[192:195], v[200:203], v[122:125]
	v_mfma_f32_16x16x32_bf16 v[110:113], v[158:161], v[208:211], v[110:113]
	v_mfma_f32_16x16x32_bf16 v[106:109], v[192:195], v[208:211], v[106:109]
	v_mfma_f32_16x16x32_bf16 v[94:97], v[158:161], v[216:219], v[94:97]
	v_mfma_f32_16x16x32_bf16 v[90:93], v[192:195], v[216:219], v[90:93]
	v_mfma_f32_16x16x32_bf16 v[78:81], v[158:161], v[224:227], v[78:81]
	v_mfma_f32_16x16x32_bf16 v[74:77], v[192:195], v[224:227], v[74:77]
	s_setprio 0
	s_barrier
	s_add_i32 s50, 0, 0x1c000
	s_add_i32 s51, s64, s28
	v_add_u32_e32 v167, s50, v164
	v_lshl_add_u64 v[162:163], v[162:163], 0, s[4:5]
	s_mov_b32 m0, s51
	ds_read_b128 v[228:231], v167
	ds_read_b128 v[232:235], v167 offset:1024
	ds_read_b128 v[236:239], v167 offset:2048
	ds_read_b128 v[240:243], v167 offset:3072
	global_load_lds_dwordx4 v[162:163], off
	v_lshl_add_u64 v[162:163], v[178:179], 0, s[4:5]
	s_add_i32 m0, s51, 0x2000
	s_nop 0
	global_load_lds_dwordx4 v[162:163], off
	s_barrier
	s_waitcnt lgkmcnt(0)
	s_setprio 1
	s_waitcnt lgkmcnt(0)
	v_mfma_f32_16x16x32_bf16 v[118:121], v[228:231], v[196:199], v[118:121]
	v_mfma_f32_16x16x32_bf16 v[114:117], v[236:239], v[196:199], v[114:117]
	v_mfma_f32_16x16x32_bf16 v[102:105], v[228:231], v[204:207], v[102:105]
	v_mfma_f32_16x16x32_bf16 v[98:101], v[236:239], v[204:207], v[98:101]
	v_mfma_f32_16x16x32_bf16 v[86:89], v[228:231], v[212:215], v[86:89]
	v_mfma_f32_16x16x32_bf16 v[82:85], v[236:239], v[212:215], v[82:85]
	v_mfma_f32_16x16x32_bf16 v[70:73], v[228:231], v[220:223], v[70:73]
	v_mfma_f32_16x16x32_bf16 v[66:69], v[236:239], v[220:223], v[66:69]
	v_mfma_f32_16x16x32_bf16 v[118:121], v[232:235], v[200:203], v[118:121]
	v_mfma_f32_16x16x32_bf16 v[114:117], v[240:243], v[200:203], v[114:117]
	v_mfma_f32_16x16x32_bf16 v[102:105], v[232:235], v[208:211], v[102:105]
	v_mfma_f32_16x16x32_bf16 v[98:101], v[240:243], v[208:211], v[98:101]
	v_mfma_f32_16x16x32_bf16 v[86:89], v[232:235], v[216:219], v[86:89]
	v_mfma_f32_16x16x32_bf16 v[82:85], v[240:243], v[216:219], v[82:85]
	v_mfma_f32_16x16x32_bf16 v[70:73], v[232:235], v[224:227], v[70:73]
	v_mfma_f32_16x16x32_bf16 v[66:69], v[240:243], v[224:227], v[66:69]
	s_setprio 0
	s_mov_b32 m0, s56
	v_lshl_add_u64 v[162:163], v[244:245], 0, s[4:5]
	s_barrier
	ds_read_b128 v[196:199], v166 offset:49152
	ds_read_b128 v[200:203], v166 offset:50176
	ds_read_b128 v[204:207], v166 offset:51200
	ds_read_b128 v[208:211], v166 offset:52224
	ds_read_b128 v[212:215], v166 offset:53248
	ds_read_b128 v[216:219], v166 offset:54272
	ds_read_b128 v[220:223], v166 offset:55296
	ds_read_b128 v[224:227], v166 offset:56320
	global_load_lds_dwordx4 v[162:163], off
	v_lshl_add_u64 v[162:163], v[246:247], 0, s[4:5]
	s_mov_b32 m0, s57
	s_nop 0
	global_load_lds_dwordx4 v[162:163], off
	s_barrier
; #define PG8_STAGE(bufoff, gbase, voff) do { _Pragma("unroll") for (int _i = 0; _i < 2; ++_i) \
;     __builtin_amdgcn_global_load_lds((const unsigned*)((const char*)(gbase) + (voff)[_i]), (PG8_LAS unsigned*)(lds + (bufoff) + ldsw + _i * 8192), 16, 0, 0); } while (0)
; #define PG8_MMA(ai, bj, At, Bt) do { __builtin_amdgcn_s_setprio(1); _Pragma("unroll") for (int m = 0; m < 4; ++m) _Pragma("unroll") for (int n = 0; n < 2; ++n) _Pragma("unroll") for (int k = 0; k < 2; ++k) \
;     acc[ai][bj][m][n] = __builtin_amdgcn_mfma_f32_16x16x32_bf16(Bt[n][k], At[m][k], acc[ai][bj][m][n], 0, 0, 0); __builtin_amdgcn_s_setprio(0); } while (0)
; #define PG8_WAIT_V(n) asm volatile("s_waitcnt vmcnt(" #n ")" ::: "memory")
; #define PG8_WAIT_L(n) asm volatile("s_waitcnt lgkmcnt(" #n ")" ::: "memory")
; #define PG8_BAR __builtin_amdgcn_s_barrier()
; #define PG8_SCHED __builtin_amdgcn_sched_barrier(0)
; template <class Epi>
; __device__ __forceinline__ void gemm_phase(PG8_LAS unsigned char* lds, const Gemm g, const StaticOrder& S, const Epi& E) {
;     ...
;       PG8_BAR; PG8_WAIT_L(0); PG8_MMA(1, 0, At, B0); PG8_BAR; PG8_SCHED;
;       PG8_STAGE(PG8_SB(1, 1), b3 + hstep, voffB);
;       PG8_WAIT_V(6); PG8_BAR; PG8_MMA(1, 1, At, B1); PG8_BAR;
	s_waitcnt lgkmcnt(0)
	s_setprio 1
	s_waitcnt lgkmcnt(0)
	v_mfma_f32_16x16x32_bf16 v[62:65], v[154:157], v[196:199], v[62:65]
	v_mfma_f32_16x16x32_bf16 v[58:61], v[188:191], v[196:199], v[58:61]
	v_mfma_f32_16x16x32_bf16 v[46:49], v[154:157], v[204:207], v[46:49]
	v_mfma_f32_16x16x32_bf16 v[42:45], v[188:191], v[204:207], v[42:45]
	v_mfma_f32_16x16x32_bf16 v[30:33], v[154:157], v[212:215], v[30:33]
	v_mfma_f32_16x16x32_bf16 v[26:29], v[188:191], v[212:215], v[26:29]
	v_mfma_f32_16x16x32_bf16 v[14:17], v[154:157], v[220:223], v[14:17]
	v_mfma_f32_16x16x32_bf16 v[10:13], v[188:191], v[220:223], v[10:13]
	v_mfma_f32_16x16x32_bf16 v[62:65], v[158:161], v[200:203], v[62:65]
	v_mfma_f32_16x16x32_bf16 v[58:61], v[192:195], v[200:203], v[58:61]
	v_mfma_f32_16x16x32_bf16 v[46:49], v[158:161], v[208:211], v[46:49]
	v_mfma_f32_16x16x32_bf16 v[42:45], v[192:195], v[208:211], v[42:45]
	v_mfma_f32_16x16x32_bf16 v[30:33], v[158:161], v[216:219], v[30:33]
	v_mfma_f32_16x16x32_bf16 v[26:29], v[192:195], v[216:219], v[26:29]
	v_mfma_f32_16x16x32_bf16 v[14:17], v[158:161], v[224:227], v[14:17]
	v_mfma_f32_16x16x32_bf16 v[10:13], v[192:195], v[224:227], v[10:13]
	s_setprio 0
	s_barrier
	s_add_u32 s10, s10, 0x40080
	s_addc_u32 s11, s11, 0
	s_add_i32 s50, s50, s28
	v_lshl_add_u64 v[154:155], s[10:11], 0, v[0:1]
	s_mov_b32 m0, s50
	s_nop 0
	global_load_lds_dwordx4 v[154:155], off
	v_lshl_add_u64 v[154:155], s[10:11], 0, v[148:149]
	s_add_i32 m0, s50, 0x2000
	s_nop 0
	global_load_lds_dwordx4 v[154:155], off
	s_waitcnt vmcnt(6)
	s_barrier
	s_setprio 1
	v_mfma_f32_16x16x32_bf16 v[54:57], v[228:231], v[196:199], v[54:57]
	v_mfma_f32_16x16x32_bf16 v[50:53], v[236:239], v[196:199], v[50:53]
	v_mfma_f32_16x16x32_bf16 v[38:41], v[228:231], v[204:207], v[38:41]
	v_mfma_f32_16x16x32_bf16 v[34:37], v[236:239], v[204:207], v[34:37]
	v_mfma_f32_16x16x32_bf16 v[22:25], v[228:231], v[212:215], v[22:25]
	v_mfma_f32_16x16x32_bf16 v[18:21], v[236:239], v[212:215], v[18:21]
	v_mfma_f32_16x16x32_bf16 v[6:9], v[228:231], v[220:223], v[6:9]
	v_mfma_f32_16x16x32_bf16 v[2:5], v[236:239], v[220:223], v[2:5]
	v_mfma_f32_16x16x32_bf16 v[54:57], v[232:235], v[200:203], v[54:57]
	v_mfma_f32_16x16x32_bf16 v[50:53], v[240:243], v[200:203], v[50:53]
	v_mfma_f32_16x16x32_bf16 v[38:41], v[232:235], v[208:211], v[38:41]
	v_mfma_f32_16x16x32_bf16 v[34:37], v[240:243], v[208:211], v[34:37]
	v_mfma_f32_16x16x32_bf16 v[22:25], v[232:235], v[216:219], v[22:25]
	v_mfma_f32_16x16x32_bf16 v[18:21], v[240:243], v[216:219], v[18:21]
	v_mfma_f32_16x16x32_bf16 v[6:9], v[232:235], v[224:227], v[6:9]
	v_mfma_f32_16x16x32_bf16 v[2:5], v[240:243], v[224:227], v[2:5]
	s_setprio 0
	s_add_i32 s63, s63, 2
	s_add_u32 s8, s8, 0x100
	s_addc_u32 s9, s9, 0
	s_add_u32 s61, s61, 0x100
	s_addc_u32 s62, s62, 0
	s_cmp_gt_u32 s63, 13
	s_barrier
	s_cbranch_scc0 .LBB0_1123
	v_lshl_add_u32 v154, s7, 8, v147
	v_lshl_or_b32 v160, s6, 8, v165
	v_readlane_b32 s8, v251, 37
	v_readlane_b32 s9, v251, 38
	s_lshl_b32 s50, s6, 2
	s_mov_b32 s51, 0
	s_mov_b32 s6, s42
	s_mov_b32 s7, s44
	s_mov_b64 s[10:11], s[48:49]
	v_mov_b32_e32 v155, 0
	v_mov_b32_e32 v161, 0
	v_lshlrev_b32_e32 v162, 2, v160
	v_mov_b32_e32 v163, 0
	v_lshl_add_u64 v[162:163], v[162:163], 0, s[30:31]
	global_load_dwordx4 v[228:231], v[162:163], off
	global_load_dwordx4 v[232:235], v[162:163], off offset:64
	global_load_dwordx4 v[236:239], v[162:163], off offset:512
	global_load_dwordx4 v[240:243], v[162:163], off offset:576
	s_add_u32 s8, s8, s50
	s_addc_u32 s9, s9, 0
	v_lshlrev_b32_e32 v178, 5, v154
	v_mov_b32_e32 v179, 0
	v_lshl_add_u64 v[222:223], v[178:179], 0, s[8:9]
	v_add_co_u32_e32 v224, vcc, 0x1000, v222
	s_nop 1
	v_addc_co_u32_e32 v225, vcc, 0, v223, vcc
	v_lshlrev_b32_e32 v154, 12, v154
	v_lshl_add_u32 v154, v160, 1, v154
	v_lshl_add_u64 v[220:221], v[154:155], 0, s[90:91]
	v_mov_b64_e32 v[156:157], v[220:221]
	global_load_dword v188, v[222:223], off
	global_load_dwordx2 v[190:191], v[156:157], off
	global_load_dwordx2 v[192:193], v[156:157], off offset:32
	global_load_dwordx2 v[194:195], v[156:157], off offset:256
	global_load_dwordx2 v[196:197], v[156:157], off offset:288
	v_add_co_u32_e32 v158, vcc, 0x10000, v220
	s_nop 1
	v_addc_co_u32_e32 v159, vcc, 0, v221, vcc
	global_load_dword v198, v[222:223], off offset:512
	global_load_dwordx2 v[200:201], v[158:159], off
	global_load_dwordx2 v[202:203], v[158:159], off offset:32
	global_load_dwordx2 v[204:205], v[158:159], off offset:256
	global_load_dwordx2 v[206:207], v[158:159], off offset:288
	s_waitcnt vmcnt(5)
	v_mul_f32_e32 v208, 0xbfb8aa3b, v126
	v_mul_f32_e32 v209, 0xbfb8aa3b, v127
	v_mul_f32_e32 v210, 0xbfb8aa3b, v128
	v_mul_f32_e32 v211, 0xbfb8aa3b, v129
	v_exp_f32_e32 v208, v208
	v_exp_f32_e32 v209, v209
	v_exp_f32_e32 v210, v210
	v_exp_f32_e32 v211, v211
	v_add_f32_e32 v208, 1.0, v208
	v_add_f32_e32 v209, 1.0, v209
	v_add_f32_e32 v210, 1.0, v210
	v_add_f32_e32 v211, 1.0, v211
	v_rcp_f32_e32 v208, v208
	v_rcp_f32_e32 v209, v209
	v_rcp_f32_e32 v210, v210
	v_rcp_f32_e32 v211, v211
	v_lshlrev_b32_e32 v212, 16, v190
	v_and_b32_e32 v213, 0xffff0000, v190
	v_lshlrev_b32_e32 v214, 16, v191
	v_and_b32_e32 v215, 0xffff0000, v191
	v_pk_mul_f32 v[126:127], v[126:127], v[208:209]
	v_pk_mul_f32 v[128:129], v[128:129], v[210:211]
	v_pk_mul_f32 v[212:213], v[188:189], v[212:213] op_sel_hi:[0,1]
	v_pk_mul_f32 v[214:215], v[188:189], v[214:215] op_sel_hi:[0,1]
	v_pk_mul_f32 v[212:213], v[212:213], v[228:229]
	v_pk_mul_f32 v[214:215], v[214:215], v[230:231]
	v_pk_mul_f32 v[126:127], v[126:127], v[212:213]
	v_pk_mul_f32 v[128:129], v[128:129], v[214:215]
	v_cvt_pk_bf16_f32 v126, v126, v127
	v_cvt_pk_bf16_f32 v127, v128, v129
	v_mul_f32_e32 v208, 0xbfb8aa3b, v122
	v_mul_f32_e32 v209, 0xbfb8aa3b, v123
	v_mul_f32_e32 v210, 0xbfb8aa3b, v124
	v_mul_f32_e32 v211, 0xbfb8aa3b, v125
	v_exp_f32_e32 v208, v208
	v_exp_f32_e32 v209, v209
	v_exp_f32_e32 v210, v210
	v_exp_f32_e32 v211, v211
	v_add_f32_e32 v208, 1.0, v208
	v_add_f32_e32 v209, 1.0, v209
	v_add_f32_e32 v210, 1.0, v210
	v_add_f32_e32 v211, 1.0, v211
	v_rcp_f32_e32 v208, v208
	v_rcp_f32_e32 v209, v209
	v_rcp_f32_e32 v210, v210
	v_rcp_f32_e32 v211, v211
	v_lshlrev_b32_e32 v212, 16, v192
	v_and_b32_e32 v213, 0xffff0000, v192
	v_lshlrev_b32_e32 v214, 16, v193
	v_and_b32_e32 v215, 0xffff0000, v193
	v_pk_mul_f32 v[122:123], v[122:123], v[208:209]
	v_pk_mul_f32 v[124:125], v[124:125], v[210:211]
	v_pk_mul_f32 v[212:213], v[188:189], v[212:213] op_sel_hi:[0,1]
	v_pk_mul_f32 v[214:215], v[188:189], v[214:215] op_sel_hi:[0,1]
	v_pk_mul_f32 v[212:213], v[212:213], v[232:233]
	v_pk_mul_f32 v[214:215], v[214:215], v[234:235]
	v_pk_mul_f32 v[122:123], v[122:123], v[212:213]
	v_pk_mul_f32 v[124:125], v[124:125], v[214:215]
	v_cvt_pk_bf16_f32 v122, v122, v123
	v_cvt_pk_bf16_f32 v123, v124, v125
	v_mul_f32_e32 v208, 0xbfb8aa3b, v118
	v_mul_f32_e32 v209, 0xbfb8aa3b, v119
	v_mul_f32_e32 v210, 0xbfb8aa3b, v120
	v_mul_f32_e32 v211, 0xbfb8aa3b, v121
	v_exp_f32_e32 v208, v208
	v_exp_f32_e32 v209, v209
	v_exp_f32_e32 v210, v210
	v_exp_f32_e32 v211, v211
	v_add_f32_e32 v208, 1.0, v208
	v_add_f32_e32 v209, 1.0, v209
	v_add_f32_e32 v210, 1.0, v210
	v_add_f32_e32 v211, 1.0, v211
	v_rcp_f32_e32 v208, v208
	v_rcp_f32_e32 v209, v209
	v_rcp_f32_e32 v210, v210
	v_rcp_f32_e32 v211, v211
	v_lshlrev_b32_e32 v212, 16, v194
	v_and_b32_e32 v213, 0xffff0000, v194
	v_lshlrev_b32_e32 v214, 16, v195
	v_and_b32_e32 v215, 0xffff0000, v195
	v_pk_mul_f32 v[118:119], v[118:119], v[208:209]
	v_pk_mul_f32 v[120:121], v[120:121], v[210:211]
	v_pk_mul_f32 v[212:213], v[188:189], v[212:213] op_sel_hi:[0,1]
	v_pk_mul_f32 v[214:215], v[188:189], v[214:215] op_sel_hi:[0,1]
	v_pk_mul_f32 v[212:213], v[212:213], v[236:237]
	v_pk_mul_f32 v[214:215], v[214:215], v[238:239]
	v_pk_mul_f32 v[118:119], v[118:119], v[212:213]
	v_pk_mul_f32 v[120:121], v[120:121], v[214:215]
	v_cvt_pk_bf16_f32 v118, v118, v119
	v_cvt_pk_bf16_f32 v119, v120, v121
	v_mul_f32_e32 v208, 0xbfb8aa3b, v114
	v_mul_f32_e32 v209, 0xbfb8aa3b, v115
	v_mul_f32_e32 v210, 0xbfb8aa3b, v116
	v_mul_f32_e32 v211, 0xbfb8aa3b, v117
	v_exp_f32_e32 v208, v208
	v_exp_f32_e32 v209, v209
	v_exp_f32_e32 v210, v210
	v_exp_f32_e32 v211, v211
	v_add_f32_e32 v208, 1.0, v208
	v_add_f32_e32 v209, 1.0, v209
	v_add_f32_e32 v210, 1.0, v210
	v_add_f32_e32 v211, 1.0, v211
	v_rcp_f32_e32 v208, v208
	v_rcp_f32_e32 v209, v209
	v_rcp_f32_e32 v210, v210
	v_rcp_f32_e32 v211, v211
	v_lshlrev_b32_e32 v212, 16, v196
	v_and_b32_e32 v213, 0xffff0000, v196
	v_lshlrev_b32_e32 v214, 16, v197
	v_and_b32_e32 v215, 0xffff0000, v197
	v_pk_mul_f32 v[114:115], v[114:115], v[208:209]
	v_pk_mul_f32 v[116:117], v[116:117], v[210:211]
	v_pk_mul_f32 v[212:213], v[188:189], v[212:213] op_sel_hi:[0,1]
	v_pk_mul_f32 v[214:215], v[188:189], v[214:215] op_sel_hi:[0,1]
	v_pk_mul_f32 v[212:213], v[212:213], v[240:241]
	v_pk_mul_f32 v[214:215], v[214:215], v[242:243]
	v_pk_mul_f32 v[114:115], v[114:115], v[212:213]
	v_pk_mul_f32 v[116:117], v[116:117], v[214:215]
	v_cvt_pk_bf16_f32 v114, v114, v115
	v_cvt_pk_bf16_f32 v115, v116, v117
	global_store_dwordx2 v[156:157], v[126:127], off
	global_store_dwordx2 v[156:157], v[122:123], off offset:32
	global_store_dwordx2 v[156:157], v[118:119], off offset:256
	global_store_dwordx2 v[156:157], v[114:115], off offset:288
	v_add_co_u32_e32 v156, vcc, 0x20000, v220
	s_nop 1
	v_addc_co_u32_e32 v157, vcc, 0, v221, vcc
	global_load_dword v128, v[222:223], off offset:1024
	global_load_dwordx2 v[126:127], v[156:157], off
	global_load_dwordx2 v[122:123], v[156:157], off offset:32
	global_load_dwordx2 v[118:119], v[156:157], off offset:256
	global_load_dwordx2 v[114:115], v[156:157], off offset:288
	s_waitcnt vmcnt(9)
	v_mul_f32_e32 v208, 0xbfb8aa3b, v110
	v_mul_f32_e32 v209, 0xbfb8aa3b, v111
	v_mul_f32_e32 v210, 0xbfb8aa3b, v112
	v_mul_f32_e32 v211, 0xbfb8aa3b, v113
	v_exp_f32_e32 v208, v208
	v_exp_f32_e32 v209, v209
	v_exp_f32_e32 v210, v210
	v_exp_f32_e32 v211, v211
	v_add_f32_e32 v208, 1.0, v208
	v_add_f32_e32 v209, 1.0, v209
	v_add_f32_e32 v210, 1.0, v210
	v_add_f32_e32 v211, 1.0, v211
	v_rcp_f32_e32 v208, v208
	v_rcp_f32_e32 v209, v209
	v_rcp_f32_e32 v210, v210
	v_rcp_f32_e32 v211, v211
	v_lshlrev_b32_e32 v212, 16, v200
	v_and_b32_e32 v213, 0xffff0000, v200
	v_lshlrev_b32_e32 v214, 16, v201
	v_and_b32_e32 v215, 0xffff0000, v201
	v_pk_mul_f32 v[110:111], v[110:111], v[208:209]
	v_pk_mul_f32 v[112:113], v[112:113], v[210:211]
	v_pk_mul_f32 v[212:213], v[198:199], v[212:213] op_sel_hi:[0,1]
	v_pk_mul_f32 v[214:215], v[198:199], v[214:215] op_sel_hi:[0,1]
	v_pk_mul_f32 v[212:213], v[212:213], v[228:229]
	v_pk_mul_f32 v[214:215], v[214:215], v[230:231]
	v_pk_mul_f32 v[110:111], v[110:111], v[212:213]
	v_pk_mul_f32 v[112:113], v[112:113], v[214:215]
	v_cvt_pk_bf16_f32 v110, v110, v111
	v_cvt_pk_bf16_f32 v111, v112, v113
	v_mul_f32_e32 v208, 0xbfb8aa3b, v106
	v_mul_f32_e32 v209, 0xbfb8aa3b, v107
	v_mul_f32_e32 v210, 0xbfb8aa3b, v108
	v_mul_f32_e32 v211, 0xbfb8aa3b, v109
	v_exp_f32_e32 v208, v208
	v_exp_f32_e32 v209, v209
	v_exp_f32_e32 v210, v210
	v_exp_f32_e32 v211, v211
	v_add_f32_e32 v208, 1.0, v208
	v_add_f32_e32 v209, 1.0, v209
	v_add_f32_e32 v210, 1.0, v210
	v_add_f32_e32 v211, 1.0, v211
	v_rcp_f32_e32 v208, v208
	v_rcp_f32_e32 v209, v209
	v_rcp_f32_e32 v210, v210
	v_rcp_f32_e32 v211, v211
	v_lshlrev_b32_e32 v212, 16, v202
	v_and_b32_e32 v213, 0xffff0000, v202
	v_lshlrev_b32_e32 v214, 16, v203
	v_and_b32_e32 v215, 0xffff0000, v203
	v_pk_mul_f32 v[106:107], v[106:107], v[208:209]
	v_pk_mul_f32 v[108:109], v[108:109], v[210:211]
	v_pk_mul_f32 v[212:213], v[198:199], v[212:213] op_sel_hi:[0,1]
	v_pk_mul_f32 v[214:215], v[198:199], v[214:215] op_sel_hi:[0,1]
	v_pk_mul_f32 v[212:213], v[212:213], v[232:233]
	v_pk_mul_f32 v[214:215], v[214:215], v[234:235]
	v_pk_mul_f32 v[106:107], v[106:107], v[212:213]
	v_pk_mul_f32 v[108:109], v[108:109], v[214:215]
	v_cvt_pk_bf16_f32 v106, v106, v107
	v_cvt_pk_bf16_f32 v107, v108, v109
	v_mul_f32_e32 v208, 0xbfb8aa3b, v102
	v_mul_f32_e32 v209, 0xbfb8aa3b, v103
	v_mul_f32_e32 v210, 0xbfb8aa3b, v104
	v_mul_f32_e32 v211, 0xbfb8aa3b, v105
	v_exp_f32_e32 v208, v208
	v_exp_f32_e32 v209, v209
	v_exp_f32_e32 v210, v210
	v_exp_f32_e32 v211, v211
	v_add_f32_e32 v208, 1.0, v208
	v_add_f32_e32 v209, 1.0, v209
	v_add_f32_e32 v210, 1.0, v210
	v_add_f32_e32 v211, 1.0, v211
	v_rcp_f32_e32 v208, v208
	v_rcp_f32_e32 v209, v209
	v_rcp_f32_e32 v210, v210
	v_rcp_f32_e32 v211, v211
	v_lshlrev_b32_e32 v212, 16, v204
	v_and_b32_e32 v213, 0xffff0000, v204
	v_lshlrev_b32_e32 v214, 16, v205
	v_and_b32_e32 v215, 0xffff0000, v205
	v_pk_mul_f32 v[102:103], v[102:103], v[208:209]
	v_pk_mul_f32 v[104:105], v[104:105], v[210:211]
	v_pk_mul_f32 v[212:213], v[198:199], v[212:213] op_sel_hi:[0,1]
	v_pk_mul_f32 v[214:215], v[198:199], v[214:215] op_sel_hi:[0,1]
	v_pk_mul_f32 v[212:213], v[212:213], v[236:237]
	v_pk_mul_f32 v[214:215], v[214:215], v[238:239]
	v_pk_mul_f32 v[102:103], v[102:103], v[212:213]
	v_pk_mul_f32 v[104:105], v[104:105], v[214:215]
	v_cvt_pk_bf16_f32 v102, v102, v103
	v_cvt_pk_bf16_f32 v103, v104, v105
	v_mul_f32_e32 v208, 0xbfb8aa3b, v98
	v_mul_f32_e32 v209, 0xbfb8aa3b, v99
	v_mul_f32_e32 v210, 0xbfb8aa3b, v100
	v_mul_f32_e32 v211, 0xbfb8aa3b, v101
	v_exp_f32_e32 v208, v208
	v_exp_f32_e32 v209, v209
	v_exp_f32_e32 v210, v210
	v_exp_f32_e32 v211, v211
	v_add_f32_e32 v208, 1.0, v208
	v_add_f32_e32 v209, 1.0, v209
	v_add_f32_e32 v210, 1.0, v210
	v_add_f32_e32 v211, 1.0, v211
	v_rcp_f32_e32 v208, v208
	v_rcp_f32_e32 v209, v209
	v_rcp_f32_e32 v210, v210
	v_rcp_f32_e32 v211, v211
	v_lshlrev_b32_e32 v212, 16, v206
	v_and_b32_e32 v213, 0xffff0000, v206
	v_lshlrev_b32_e32 v214, 16, v207
	v_and_b32_e32 v215, 0xffff0000, v207
	v_pk_mul_f32 v[98:99], v[98:99], v[208:209]
	v_pk_mul_f32 v[100:101], v[100:101], v[210:211]
	v_pk_mul_f32 v[212:213], v[198:199], v[212:213] op_sel_hi:[0,1]
	v_pk_mul_f32 v[214:215], v[198:199], v[214:215] op_sel_hi:[0,1]
	v_pk_mul_f32 v[212:213], v[212:213], v[240:241]
	v_pk_mul_f32 v[214:215], v[214:215], v[242:243]
	v_pk_mul_f32 v[98:99], v[98:99], v[212:213]
	v_pk_mul_f32 v[100:101], v[100:101], v[214:215]
	v_cvt_pk_bf16_f32 v98, v98, v99
	v_cvt_pk_bf16_f32 v99, v100, v101
	global_store_dwordx2 v[158:159], v[110:111], off
	global_store_dwordx2 v[158:159], v[106:107], off offset:32
	global_store_dwordx2 v[158:159], v[102:103], off offset:256
	global_store_dwordx2 v[158:159], v[98:99], off offset:288
	v_add_co_u32_e32 v158, vcc, 0x30000, v220
	s_nop 1
	v_addc_co_u32_e32 v159, vcc, 0, v221, vcc
	global_load_dword v112, v[222:223], off offset:1536
	global_load_dwordx2 v[110:111], v[158:159], off
	global_load_dwordx2 v[106:107], v[158:159], off offset:32
	global_load_dwordx2 v[102:103], v[158:159], off offset:256
	global_load_dwordx2 v[98:99], v[158:159], off offset:288
	s_waitcnt vmcnt(9)
	v_mul_f32_e32 v208, 0xbfb8aa3b, v94
	v_mul_f32_e32 v209, 0xbfb8aa3b, v95
	v_mul_f32_e32 v210, 0xbfb8aa3b, v96
	v_mul_f32_e32 v211, 0xbfb8aa3b, v97
	v_exp_f32_e32 v208, v208
	v_exp_f32_e32 v209, v209
	v_exp_f32_e32 v210, v210
	v_exp_f32_e32 v211, v211
	v_add_f32_e32 v208, 1.0, v208
	v_add_f32_e32 v209, 1.0, v209
	v_add_f32_e32 v210, 1.0, v210
	v_add_f32_e32 v211, 1.0, v211
	v_rcp_f32_e32 v208, v208
	v_rcp_f32_e32 v209, v209
	v_rcp_f32_e32 v210, v210
	v_rcp_f32_e32 v211, v211
	v_lshlrev_b32_e32 v212, 16, v126
	v_and_b32_e32 v213, 0xffff0000, v126
	v_lshlrev_b32_e32 v214, 16, v127
	v_and_b32_e32 v215, 0xffff0000, v127
	v_pk_mul_f32 v[94:95], v[94:95], v[208:209]
	v_pk_mul_f32 v[96:97], v[96:97], v[210:211]
	v_pk_mul_f32 v[212:213], v[128:129], v[212:213] op_sel_hi:[0,1]
	v_pk_mul_f32 v[214:215], v[128:129], v[214:215] op_sel_hi:[0,1]
	v_pk_mul_f32 v[212:213], v[212:213], v[228:229]
	v_pk_mul_f32 v[214:215], v[214:215], v[230:231]
	v_pk_mul_f32 v[94:95], v[94:95], v[212:213]
	v_pk_mul_f32 v[96:97], v[96:97], v[214:215]
	v_cvt_pk_bf16_f32 v94, v94, v95
	v_cvt_pk_bf16_f32 v95, v96, v97
	v_mul_f32_e32 v208, 0xbfb8aa3b, v90
	v_mul_f32_e32 v209, 0xbfb8aa3b, v91
	v_mul_f32_e32 v210, 0xbfb8aa3b, v92
	v_mul_f32_e32 v211, 0xbfb8aa3b, v93
	v_exp_f32_e32 v208, v208
	v_exp_f32_e32 v209, v209
	v_exp_f32_e32 v210, v210
	v_exp_f32_e32 v211, v211
	v_add_f32_e32 v208, 1.0, v208
	v_add_f32_e32 v209, 1.0, v209
	v_add_f32_e32 v210, 1.0, v210
	v_add_f32_e32 v211, 1.0, v211
	v_rcp_f32_e32 v208, v208
	v_rcp_f32_e32 v209, v209
	v_rcp_f32_e32 v210, v210
	v_rcp_f32_e32 v211, v211
	v_lshlrev_b32_e32 v212, 16, v122
	v_and_b32_e32 v213, 0xffff0000, v122
	v_lshlrev_b32_e32 v214, 16, v123
	v_and_b32_e32 v215, 0xffff0000, v123
	v_pk_mul_f32 v[90:91], v[90:91], v[208:209]
	v_pk_mul_f32 v[92:93], v[92:93], v[210:211]
	v_pk_mul_f32 v[212:213], v[128:129], v[212:213] op_sel_hi:[0,1]
	v_pk_mul_f32 v[214:215], v[128:129], v[214:215] op_sel_hi:[0,1]
	v_pk_mul_f32 v[212:213], v[212:213], v[232:233]
	v_pk_mul_f32 v[214:215], v[214:215], v[234:235]
	v_pk_mul_f32 v[90:91], v[90:91], v[212:213]
	v_pk_mul_f32 v[92:93], v[92:93], v[214:215]
	v_cvt_pk_bf16_f32 v90, v90, v91
	v_cvt_pk_bf16_f32 v91, v92, v93
	v_mul_f32_e32 v208, 0xbfb8aa3b, v86
	v_mul_f32_e32 v209, 0xbfb8aa3b, v87
	v_mul_f32_e32 v210, 0xbfb8aa3b, v88
	v_mul_f32_e32 v211, 0xbfb8aa3b, v89
	v_exp_f32_e32 v208, v208
	v_exp_f32_e32 v209, v209
	v_exp_f32_e32 v210, v210
	v_exp_f32_e32 v211, v211
	v_add_f32_e32 v208, 1.0, v208
	v_add_f32_e32 v209, 1.0, v209
	v_add_f32_e32 v210, 1.0, v210
	v_add_f32_e32 v211, 1.0, v211
	v_rcp_f32_e32 v208, v208
	v_rcp_f32_e32 v209, v209
	v_rcp_f32_e32 v210, v210
	v_rcp_f32_e32 v211, v211
	v_lshlrev_b32_e32 v212, 16, v118
	v_and_b32_e32 v213, 0xffff0000, v118
	v_lshlrev_b32_e32 v214, 16, v119
	v_and_b32_e32 v215, 0xffff0000, v119
	v_pk_mul_f32 v[86:87], v[86:87], v[208:209]
	v_pk_mul_f32 v[88:89], v[88:89], v[210:211]
	v_pk_mul_f32 v[212:213], v[128:129], v[212:213] op_sel_hi:[0,1]
	v_pk_mul_f32 v[214:215], v[128:129], v[214:215] op_sel_hi:[0,1]
	v_pk_mul_f32 v[212:213], v[212:213], v[236:237]
	v_pk_mul_f32 v[214:215], v[214:215], v[238:239]
	v_pk_mul_f32 v[86:87], v[86:87], v[212:213]
	v_pk_mul_f32 v[88:89], v[88:89], v[214:215]
	v_cvt_pk_bf16_f32 v86, v86, v87
	v_cvt_pk_bf16_f32 v87, v88, v89
	v_mul_f32_e32 v208, 0xbfb8aa3b, v82
	v_mul_f32_e32 v209, 0xbfb8aa3b, v83
	v_mul_f32_e32 v210, 0xbfb8aa3b, v84
	v_mul_f32_e32 v211, 0xbfb8aa3b, v85
	v_exp_f32_e32 v208, v208
	v_exp_f32_e32 v209, v209
	v_exp_f32_e32 v210, v210
	v_exp_f32_e32 v211, v211
	v_add_f32_e32 v208, 1.0, v208
	v_add_f32_e32 v209, 1.0, v209
	v_add_f32_e32 v210, 1.0, v210
	v_add_f32_e32 v211, 1.0, v211
	v_rcp_f32_e32 v208, v208
	v_rcp_f32_e32 v209, v209
	v_rcp_f32_e32 v210, v210
	v_rcp_f32_e32 v211, v211
	v_lshlrev_b32_e32 v212, 16, v114
	v_and_b32_e32 v213, 0xffff0000, v114
	v_lshlrev_b32_e32 v214, 16, v115
	v_and_b32_e32 v215, 0xffff0000, v115
	v_pk_mul_f32 v[82:83], v[82:83], v[208:209]
	v_pk_mul_f32 v[84:85], v[84:85], v[210:211]
	v_pk_mul_f32 v[212:213], v[128:129], v[212:213] op_sel_hi:[0,1]
	v_pk_mul_f32 v[214:215], v[128:129], v[214:215] op_sel_hi:[0,1]
	v_pk_mul_f32 v[212:213], v[212:213], v[240:241]
	v_pk_mul_f32 v[214:215], v[214:215], v[242:243]
	v_pk_mul_f32 v[82:83], v[82:83], v[212:213]
	v_pk_mul_f32 v[84:85], v[84:85], v[214:215]
	v_cvt_pk_bf16_f32 v82, v82, v83
	v_cvt_pk_bf16_f32 v83, v84, v85
	global_store_dwordx2 v[156:157], v[94:95], off
	global_store_dwordx2 v[156:157], v[90:91], off offset:32
	global_store_dwordx2 v[156:157], v[86:87], off offset:256
	global_store_dwordx2 v[156:157], v[82:83], off offset:288
	v_add_co_u32_e32 v156, vcc, 0x80000, v220
	s_nop 1
	v_addc_co_u32_e32 v157, vcc, 0, v221, vcc
	global_load_dword v96, v[224:225], off
	global_load_dwordx2 v[94:95], v[156:157], off
	global_load_dwordx2 v[90:91], v[156:157], off offset:32
	global_load_dwordx2 v[86:87], v[156:157], off offset:256
	global_load_dwordx2 v[82:83], v[156:157], off offset:288
	s_waitcnt vmcnt(9)
	v_mul_f32_e32 v208, 0xbfb8aa3b, v78
	v_mul_f32_e32 v209, 0xbfb8aa3b, v79
	v_mul_f32_e32 v210, 0xbfb8aa3b, v80
	v_mul_f32_e32 v211, 0xbfb8aa3b, v81
	v_exp_f32_e32 v208, v208
	v_exp_f32_e32 v209, v209
	v_exp_f32_e32 v210, v210
	v_exp_f32_e32 v211, v211
	v_add_f32_e32 v208, 1.0, v208
	v_add_f32_e32 v209, 1.0, v209
	v_add_f32_e32 v210, 1.0, v210
	v_add_f32_e32 v211, 1.0, v211
	v_rcp_f32_e32 v208, v208
	v_rcp_f32_e32 v209, v209
	v_rcp_f32_e32 v210, v210
	v_rcp_f32_e32 v211, v211
	v_lshlrev_b32_e32 v212, 16, v110
	v_and_b32_e32 v213, 0xffff0000, v110
	v_lshlrev_b32_e32 v214, 16, v111
	v_and_b32_e32 v215, 0xffff0000, v111
	v_pk_mul_f32 v[78:79], v[78:79], v[208:209]
	v_pk_mul_f32 v[80:81], v[80:81], v[210:211]
	v_pk_mul_f32 v[212:213], v[112:113], v[212:213] op_sel_hi:[0,1]
	v_pk_mul_f32 v[214:215], v[112:113], v[214:215] op_sel_hi:[0,1]
	v_pk_mul_f32 v[212:213], v[212:213], v[228:229]
	v_pk_mul_f32 v[214:215], v[214:215], v[230:231]
	v_pk_mul_f32 v[78:79], v[78:79], v[212:213]
	v_pk_mul_f32 v[80:81], v[80:81], v[214:215]
	v_cvt_pk_bf16_f32 v78, v78, v79
	v_cvt_pk_bf16_f32 v79, v80, v81
	v_mul_f32_e32 v208, 0xbfb8aa3b, v74
	v_mul_f32_e32 v209, 0xbfb8aa3b, v75
	v_mul_f32_e32 v210, 0xbfb8aa3b, v76
	v_mul_f32_e32 v211, 0xbfb8aa3b, v77
	v_exp_f32_e32 v208, v208
	v_exp_f32_e32 v209, v209
	v_exp_f32_e32 v210, v210
	v_exp_f32_e32 v211, v211
	v_add_f32_e32 v208, 1.0, v208
	v_add_f32_e32 v209, 1.0, v209
	v_add_f32_e32 v210, 1.0, v210
	v_add_f32_e32 v211, 1.0, v211
	v_rcp_f32_e32 v208, v208
	v_rcp_f32_e32 v209, v209
	v_rcp_f32_e32 v210, v210
	v_rcp_f32_e32 v211, v211
	v_lshlrev_b32_e32 v212, 16, v106
	v_and_b32_e32 v213, 0xffff0000, v106
	v_lshlrev_b32_e32 v214, 16, v107
	v_and_b32_e32 v215, 0xffff0000, v107
	v_pk_mul_f32 v[74:75], v[74:75], v[208:209]
	v_pk_mul_f32 v[76:77], v[76:77], v[210:211]
	v_pk_mul_f32 v[212:213], v[112:113], v[212:213] op_sel_hi:[0,1]
	v_pk_mul_f32 v[214:215], v[112:113], v[214:215] op_sel_hi:[0,1]
	v_pk_mul_f32 v[212:213], v[212:213], v[232:233]
	v_pk_mul_f32 v[214:215], v[214:215], v[234:235]
	v_pk_mul_f32 v[74:75], v[74:75], v[212:213]
	v_pk_mul_f32 v[76:77], v[76:77], v[214:215]
	v_cvt_pk_bf16_f32 v74, v74, v75
	v_cvt_pk_bf16_f32 v75, v76, v77
	v_mul_f32_e32 v208, 0xbfb8aa3b, v70
	v_mul_f32_e32 v209, 0xbfb8aa3b, v71
	v_mul_f32_e32 v210, 0xbfb8aa3b, v72
	v_mul_f32_e32 v211, 0xbfb8aa3b, v73
	v_exp_f32_e32 v208, v208
	v_exp_f32_e32 v209, v209
	v_exp_f32_e32 v210, v210
	v_exp_f32_e32 v211, v211
	v_add_f32_e32 v208, 1.0, v208
	v_add_f32_e32 v209, 1.0, v209
	v_add_f32_e32 v210, 1.0, v210
	v_add_f32_e32 v211, 1.0, v211
	v_rcp_f32_e32 v208, v208
	v_rcp_f32_e32 v209, v209
	v_rcp_f32_e32 v210, v210
	v_rcp_f32_e32 v211, v211
	v_lshlrev_b32_e32 v212, 16, v102
	v_and_b32_e32 v213, 0xffff0000, v102
	v_lshlrev_b32_e32 v214, 16, v103
	v_and_b32_e32 v215, 0xffff0000, v103
	v_pk_mul_f32 v[70:71], v[70:71], v[208:209]
	v_pk_mul_f32 v[72:73], v[72:73], v[210:211]
	v_pk_mul_f32 v[212:213], v[112:113], v[212:213] op_sel_hi:[0,1]
	v_pk_mul_f32 v[214:215], v[112:113], v[214:215] op_sel_hi:[0,1]
	v_pk_mul_f32 v[212:213], v[212:213], v[236:237]
	v_pk_mul_f32 v[214:215], v[214:215], v[238:239]
	v_pk_mul_f32 v[70:71], v[70:71], v[212:213]
	v_pk_mul_f32 v[72:73], v[72:73], v[214:215]
	v_cvt_pk_bf16_f32 v70, v70, v71
	v_cvt_pk_bf16_f32 v71, v72, v73
	v_mul_f32_e32 v208, 0xbfb8aa3b, v66
	v_mul_f32_e32 v209, 0xbfb8aa3b, v67
	v_mul_f32_e32 v210, 0xbfb8aa3b, v68
	v_mul_f32_e32 v211, 0xbfb8aa3b, v69
	v_exp_f32_e32 v208, v208
	v_exp_f32_e32 v209, v209
	v_exp_f32_e32 v210, v210
	v_exp_f32_e32 v211, v211
	v_add_f32_e32 v208, 1.0, v208
	v_add_f32_e32 v209, 1.0, v209
	v_add_f32_e32 v210, 1.0, v210
	v_add_f32_e32 v211, 1.0, v211
	v_rcp_f32_e32 v208, v208
	v_rcp_f32_e32 v209, v209
	v_rcp_f32_e32 v210, v210
	v_rcp_f32_e32 v211, v211
	v_lshlrev_b32_e32 v212, 16, v98
	v_and_b32_e32 v213, 0xffff0000, v98
	v_lshlrev_b32_e32 v214, 16, v99
	v_and_b32_e32 v215, 0xffff0000, v99
	v_pk_mul_f32 v[66:67], v[66:67], v[208:209]
	v_pk_mul_f32 v[68:69], v[68:69], v[210:211]
	v_pk_mul_f32 v[212:213], v[112:113], v[212:213] op_sel_hi:[0,1]
	v_pk_mul_f32 v[214:215], v[112:113], v[214:215] op_sel_hi:[0,1]
	v_pk_mul_f32 v[212:213], v[212:213], v[240:241]
	v_pk_mul_f32 v[214:215], v[214:215], v[242:243]
	v_pk_mul_f32 v[66:67], v[66:67], v[212:213]
	v_pk_mul_f32 v[68:69], v[68:69], v[214:215]
	v_cvt_pk_bf16_f32 v66, v66, v67
	v_cvt_pk_bf16_f32 v67, v68, v69
	global_store_dwordx2 v[158:159], v[78:79], off
	global_store_dwordx2 v[158:159], v[74:75], off offset:32
	global_store_dwordx2 v[158:159], v[70:71], off offset:256
	global_store_dwordx2 v[158:159], v[66:67], off offset:288
	v_add_co_u32_e32 v158, vcc, 0x90000, v220
	s_nop 1
	v_addc_co_u32_e32 v159, vcc, 0, v221, vcc
	global_load_dword v80, v[224:225], off offset:512
	global_load_dwordx2 v[78:79], v[158:159], off
	global_load_dwordx2 v[74:75], v[158:159], off offset:32
	global_load_dwordx2 v[70:71], v[158:159], off offset:256
	global_load_dwordx2 v[66:67], v[158:159], off offset:288
	s_waitcnt vmcnt(9)
	v_mul_f32_e32 v208, 0xbfb8aa3b, v62
	v_mul_f32_e32 v209, 0xbfb8aa3b, v63
	v_mul_f32_e32 v210, 0xbfb8aa3b, v64
	v_mul_f32_e32 v211, 0xbfb8aa3b, v65
	v_exp_f32_e32 v208, v208
	v_exp_f32_e32 v209, v209
	v_exp_f32_e32 v210, v210
	v_exp_f32_e32 v211, v211
	v_add_f32_e32 v208, 1.0, v208
	v_add_f32_e32 v209, 1.0, v209
	v_add_f32_e32 v210, 1.0, v210
	v_add_f32_e32 v211, 1.0, v211
	v_rcp_f32_e32 v208, v208
	v_rcp_f32_e32 v209, v209
	v_rcp_f32_e32 v210, v210
	v_rcp_f32_e32 v211, v211
	v_lshlrev_b32_e32 v212, 16, v94
	v_and_b32_e32 v213, 0xffff0000, v94
	v_lshlrev_b32_e32 v214, 16, v95
	v_and_b32_e32 v215, 0xffff0000, v95
	v_pk_mul_f32 v[62:63], v[62:63], v[208:209]
	v_pk_mul_f32 v[64:65], v[64:65], v[210:211]
	v_pk_mul_f32 v[212:213], v[96:97], v[212:213] op_sel_hi:[0,1]
	v_pk_mul_f32 v[214:215], v[96:97], v[214:215] op_sel_hi:[0,1]
	v_pk_mul_f32 v[212:213], v[212:213], v[228:229]
	v_pk_mul_f32 v[214:215], v[214:215], v[230:231]
	v_pk_mul_f32 v[62:63], v[62:63], v[212:213]
	v_pk_mul_f32 v[64:65], v[64:65], v[214:215]
	v_cvt_pk_bf16_f32 v62, v62, v63
	v_cvt_pk_bf16_f32 v63, v64, v65
	v_mul_f32_e32 v208, 0xbfb8aa3b, v58
	v_mul_f32_e32 v209, 0xbfb8aa3b, v59
	v_mul_f32_e32 v210, 0xbfb8aa3b, v60
	v_mul_f32_e32 v211, 0xbfb8aa3b, v61
	v_exp_f32_e32 v208, v208
	v_exp_f32_e32 v209, v209
	v_exp_f32_e32 v210, v210
	v_exp_f32_e32 v211, v211
	v_add_f32_e32 v208, 1.0, v208
	v_add_f32_e32 v209, 1.0, v209
	v_add_f32_e32 v210, 1.0, v210
	v_add_f32_e32 v211, 1.0, v211
	v_rcp_f32_e32 v208, v208
	v_rcp_f32_e32 v209, v209
	v_rcp_f32_e32 v210, v210
	v_rcp_f32_e32 v211, v211
	v_lshlrev_b32_e32 v212, 16, v90
	v_and_b32_e32 v213, 0xffff0000, v90
	v_lshlrev_b32_e32 v214, 16, v91
	v_and_b32_e32 v215, 0xffff0000, v91
	v_pk_mul_f32 v[58:59], v[58:59], v[208:209]
	v_pk_mul_f32 v[60:61], v[60:61], v[210:211]
	v_pk_mul_f32 v[212:213], v[96:97], v[212:213] op_sel_hi:[0,1]
	v_pk_mul_f32 v[214:215], v[96:97], v[214:215] op_sel_hi:[0,1]
	v_pk_mul_f32 v[212:213], v[212:213], v[232:233]
	v_pk_mul_f32 v[214:215], v[214:215], v[234:235]
	v_pk_mul_f32 v[58:59], v[58:59], v[212:213]
	v_pk_mul_f32 v[60:61], v[60:61], v[214:215]
	v_cvt_pk_bf16_f32 v58, v58, v59
	v_cvt_pk_bf16_f32 v59, v60, v61
	v_mul_f32_e32 v208, 0xbfb8aa3b, v54
	v_mul_f32_e32 v209, 0xbfb8aa3b, v55
	v_mul_f32_e32 v210, 0xbfb8aa3b, v56
	v_mul_f32_e32 v211, 0xbfb8aa3b, v57
	v_exp_f32_e32 v208, v208
	v_exp_f32_e32 v209, v209
	v_exp_f32_e32 v210, v210
	v_exp_f32_e32 v211, v211
	v_add_f32_e32 v208, 1.0, v208
	v_add_f32_e32 v209, 1.0, v209
	v_add_f32_e32 v210, 1.0, v210
	v_add_f32_e32 v211, 1.0, v211
	v_rcp_f32_e32 v208, v208
	v_rcp_f32_e32 v209, v209
	v_rcp_f32_e32 v210, v210
	v_rcp_f32_e32 v211, v211
	v_lshlrev_b32_e32 v212, 16, v86
	v_and_b32_e32 v213, 0xffff0000, v86
	v_lshlrev_b32_e32 v214, 16, v87
	v_and_b32_e32 v215, 0xffff0000, v87
	v_pk_mul_f32 v[54:55], v[54:55], v[208:209]
	v_pk_mul_f32 v[56:57], v[56:57], v[210:211]
	v_pk_mul_f32 v[212:213], v[96:97], v[212:213] op_sel_hi:[0,1]
	v_pk_mul_f32 v[214:215], v[96:97], v[214:215] op_sel_hi:[0,1]
	v_pk_mul_f32 v[212:213], v[212:213], v[236:237]
	v_pk_mul_f32 v[214:215], v[214:215], v[238:239]
	v_pk_mul_f32 v[54:55], v[54:55], v[212:213]
	v_pk_mul_f32 v[56:57], v[56:57], v[214:215]
	v_cvt_pk_bf16_f32 v54, v54, v55
	v_cvt_pk_bf16_f32 v55, v56, v57
	v_mul_f32_e32 v208, 0xbfb8aa3b, v50
	v_mul_f32_e32 v209, 0xbfb8aa3b, v51
	v_mul_f32_e32 v210, 0xbfb8aa3b, v52
	v_mul_f32_e32 v211, 0xbfb8aa3b, v53
	v_exp_f32_e32 v208, v208
	v_exp_f32_e32 v209, v209
	v_exp_f32_e32 v210, v210
	v_exp_f32_e32 v211, v211
	v_add_f32_e32 v208, 1.0, v208
	v_add_f32_e32 v209, 1.0, v209
	v_add_f32_e32 v210, 1.0, v210
	v_add_f32_e32 v211, 1.0, v211
	v_rcp_f32_e32 v208, v208
	v_rcp_f32_e32 v209, v209
	v_rcp_f32_e32 v210, v210
	v_rcp_f32_e32 v211, v211
	v_lshlrev_b32_e32 v212, 16, v82
	v_and_b32_e32 v213, 0xffff0000, v82
	v_lshlrev_b32_e32 v214, 16, v83
	v_and_b32_e32 v215, 0xffff0000, v83
	v_pk_mul_f32 v[50:51], v[50:51], v[208:209]
	v_pk_mul_f32 v[52:53], v[52:53], v[210:211]
	v_pk_mul_f32 v[212:213], v[96:97], v[212:213] op_sel_hi:[0,1]
	v_pk_mul_f32 v[214:215], v[96:97], v[214:215] op_sel_hi:[0,1]
	v_pk_mul_f32 v[212:213], v[212:213], v[240:241]
	v_pk_mul_f32 v[214:215], v[214:215], v[242:243]
	v_pk_mul_f32 v[50:51], v[50:51], v[212:213]
	v_pk_mul_f32 v[52:53], v[52:53], v[214:215]
	v_cvt_pk_bf16_f32 v50, v50, v51
	v_cvt_pk_bf16_f32 v51, v52, v53
	global_store_dwordx2 v[156:157], v[62:63], off
	global_store_dwordx2 v[156:157], v[58:59], off offset:32
	global_store_dwordx2 v[156:157], v[54:55], off offset:256
	global_store_dwordx2 v[156:157], v[50:51], off offset:288
	v_add_co_u32_e32 v156, vcc, 0xa0000, v220
	s_nop 1
	v_addc_co_u32_e32 v157, vcc, 0, v221, vcc
	global_load_dword v64, v[224:225], off offset:1024
	global_load_dwordx2 v[62:63], v[156:157], off
	global_load_dwordx2 v[58:59], v[156:157], off offset:32
	global_load_dwordx2 v[54:55], v[156:157], off offset:256
	global_load_dwordx2 v[50:51], v[156:157], off offset:288
	s_waitcnt vmcnt(9)
	v_mul_f32_e32 v208, 0xbfb8aa3b, v46
	v_mul_f32_e32 v209, 0xbfb8aa3b, v47
	v_mul_f32_e32 v210, 0xbfb8aa3b, v48
	v_mul_f32_e32 v211, 0xbfb8aa3b, v49
	v_exp_f32_e32 v208, v208
	v_exp_f32_e32 v209, v209
	v_exp_f32_e32 v210, v210
	v_exp_f32_e32 v211, v211
	v_add_f32_e32 v208, 1.0, v208
	v_add_f32_e32 v209, 1.0, v209
	v_add_f32_e32 v210, 1.0, v210
	v_add_f32_e32 v211, 1.0, v211
	v_rcp_f32_e32 v208, v208
	v_rcp_f32_e32 v209, v209
	v_rcp_f32_e32 v210, v210
	v_rcp_f32_e32 v211, v211
	v_lshlrev_b32_e32 v212, 16, v78
	v_and_b32_e32 v213, 0xffff0000, v78
	v_lshlrev_b32_e32 v214, 16, v79
	v_and_b32_e32 v215, 0xffff0000, v79
	v_pk_mul_f32 v[46:47], v[46:47], v[208:209]
	v_pk_mul_f32 v[48:49], v[48:49], v[210:211]
	v_pk_mul_f32 v[212:213], v[80:81], v[212:213] op_sel_hi:[0,1]
	v_pk_mul_f32 v[214:215], v[80:81], v[214:215] op_sel_hi:[0,1]
	v_pk_mul_f32 v[212:213], v[212:213], v[228:229]
	v_pk_mul_f32 v[214:215], v[214:215], v[230:231]
	v_pk_mul_f32 v[46:47], v[46:47], v[212:213]
	v_pk_mul_f32 v[48:49], v[48:49], v[214:215]
	v_cvt_pk_bf16_f32 v46, v46, v47
	v_cvt_pk_bf16_f32 v47, v48, v49
	v_mul_f32_e32 v208, 0xbfb8aa3b, v42
	v_mul_f32_e32 v209, 0xbfb8aa3b, v43
	v_mul_f32_e32 v210, 0xbfb8aa3b, v44
	v_mul_f32_e32 v211, 0xbfb8aa3b, v45
	v_exp_f32_e32 v208, v208
	v_exp_f32_e32 v209, v209
	v_exp_f32_e32 v210, v210
	v_exp_f32_e32 v211, v211
	v_add_f32_e32 v208, 1.0, v208
	v_add_f32_e32 v209, 1.0, v209
	v_add_f32_e32 v210, 1.0, v210
	v_add_f32_e32 v211, 1.0, v211
	v_rcp_f32_e32 v208, v208
	v_rcp_f32_e32 v209, v209
	v_rcp_f32_e32 v210, v210
	v_rcp_f32_e32 v211, v211
	v_lshlrev_b32_e32 v212, 16, v74
	v_and_b32_e32 v213, 0xffff0000, v74
	v_lshlrev_b32_e32 v214, 16, v75
	v_and_b32_e32 v215, 0xffff0000, v75
	v_pk_mul_f32 v[42:43], v[42:43], v[208:209]
	v_pk_mul_f32 v[44:45], v[44:45], v[210:211]
	v_pk_mul_f32 v[212:213], v[80:81], v[212:213] op_sel_hi:[0,1]
	v_pk_mul_f32 v[214:215], v[80:81], v[214:215] op_sel_hi:[0,1]
	v_pk_mul_f32 v[212:213], v[212:213], v[232:233]
	v_pk_mul_f32 v[214:215], v[214:215], v[234:235]
	v_pk_mul_f32 v[42:43], v[42:43], v[212:213]
	v_pk_mul_f32 v[44:45], v[44:45], v[214:215]
	v_cvt_pk_bf16_f32 v42, v42, v43
	v_cvt_pk_bf16_f32 v43, v44, v45
	v_mul_f32_e32 v208, 0xbfb8aa3b, v38
	v_mul_f32_e32 v209, 0xbfb8aa3b, v39
	v_mul_f32_e32 v210, 0xbfb8aa3b, v40
	v_mul_f32_e32 v211, 0xbfb8aa3b, v41
	v_exp_f32_e32 v208, v208
	v_exp_f32_e32 v209, v209
	v_exp_f32_e32 v210, v210
	v_exp_f32_e32 v211, v211
	v_add_f32_e32 v208, 1.0, v208
	v_add_f32_e32 v209, 1.0, v209
	v_add_f32_e32 v210, 1.0, v210
	v_add_f32_e32 v211, 1.0, v211
	v_rcp_f32_e32 v208, v208
	v_rcp_f32_e32 v209, v209
	v_rcp_f32_e32 v210, v210
	v_rcp_f32_e32 v211, v211
	v_lshlrev_b32_e32 v212, 16, v70
	v_and_b32_e32 v213, 0xffff0000, v70
	v_lshlrev_b32_e32 v214, 16, v71
	v_and_b32_e32 v215, 0xffff0000, v71
	v_pk_mul_f32 v[38:39], v[38:39], v[208:209]
	v_pk_mul_f32 v[40:41], v[40:41], v[210:211]
	v_pk_mul_f32 v[212:213], v[80:81], v[212:213] op_sel_hi:[0,1]
	v_pk_mul_f32 v[214:215], v[80:81], v[214:215] op_sel_hi:[0,1]
	v_pk_mul_f32 v[212:213], v[212:213], v[236:237]
	v_pk_mul_f32 v[214:215], v[214:215], v[238:239]
	v_pk_mul_f32 v[38:39], v[38:39], v[212:213]
	v_pk_mul_f32 v[40:41], v[40:41], v[214:215]
	v_cvt_pk_bf16_f32 v38, v38, v39
	v_cvt_pk_bf16_f32 v39, v40, v41
	v_mul_f32_e32 v208, 0xbfb8aa3b, v34
	v_mul_f32_e32 v209, 0xbfb8aa3b, v35
	v_mul_f32_e32 v210, 0xbfb8aa3b, v36
	v_mul_f32_e32 v211, 0xbfb8aa3b, v37
	v_exp_f32_e32 v208, v208
	v_exp_f32_e32 v209, v209
	v_exp_f32_e32 v210, v210
	v_exp_f32_e32 v211, v211
	v_add_f32_e32 v208, 1.0, v208
	v_add_f32_e32 v209, 1.0, v209
	v_add_f32_e32 v210, 1.0, v210
	v_add_f32_e32 v211, 1.0, v211
	v_rcp_f32_e32 v208, v208
	v_rcp_f32_e32 v209, v209
	v_rcp_f32_e32 v210, v210
	v_rcp_f32_e32 v211, v211
	v_lshlrev_b32_e32 v212, 16, v66
	v_and_b32_e32 v213, 0xffff0000, v66
	v_lshlrev_b32_e32 v214, 16, v67
	v_and_b32_e32 v215, 0xffff0000, v67
	v_pk_mul_f32 v[34:35], v[34:35], v[208:209]
	v_pk_mul_f32 v[36:37], v[36:37], v[210:211]
	v_pk_mul_f32 v[212:213], v[80:81], v[212:213] op_sel_hi:[0,1]
	v_pk_mul_f32 v[214:215], v[80:81], v[214:215] op_sel_hi:[0,1]
	v_pk_mul_f32 v[212:213], v[212:213], v[240:241]
	v_pk_mul_f32 v[214:215], v[214:215], v[242:243]
	v_pk_mul_f32 v[34:35], v[34:35], v[212:213]
	v_pk_mul_f32 v[36:37], v[36:37], v[214:215]
	v_cvt_pk_bf16_f32 v34, v34, v35
	v_cvt_pk_bf16_f32 v35, v36, v37
	global_store_dwordx2 v[158:159], v[46:47], off
	global_store_dwordx2 v[158:159], v[42:43], off offset:32
	global_store_dwordx2 v[158:159], v[38:39], off offset:256
	global_store_dwordx2 v[158:159], v[34:35], off offset:288
	v_add_co_u32_e32 v158, vcc, 0xb0000, v220
	s_nop 1
	v_addc_co_u32_e32 v159, vcc, 0, v221, vcc
	global_load_dword v48, v[224:225], off offset:1536
	global_load_dwordx2 v[46:47], v[158:159], off
	global_load_dwordx2 v[42:43], v[158:159], off offset:32
	global_load_dwordx2 v[38:39], v[158:159], off offset:256
	global_load_dwordx2 v[34:35], v[158:159], off offset:288
	s_waitcnt vmcnt(9)
	v_mul_f32_e32 v208, 0xbfb8aa3b, v30
	v_mul_f32_e32 v209, 0xbfb8aa3b, v31
	v_mul_f32_e32 v210, 0xbfb8aa3b, v32
	v_mul_f32_e32 v211, 0xbfb8aa3b, v33
	v_exp_f32_e32 v208, v208
	v_exp_f32_e32 v209, v209
	v_exp_f32_e32 v210, v210
	v_exp_f32_e32 v211, v211
	v_add_f32_e32 v208, 1.0, v208
	v_add_f32_e32 v209, 1.0, v209
	v_add_f32_e32 v210, 1.0, v210
	v_add_f32_e32 v211, 1.0, v211
	v_rcp_f32_e32 v208, v208
	v_rcp_f32_e32 v209, v209
	v_rcp_f32_e32 v210, v210
	v_rcp_f32_e32 v211, v211
	v_lshlrev_b32_e32 v212, 16, v62
	v_and_b32_e32 v213, 0xffff0000, v62
	v_lshlrev_b32_e32 v214, 16, v63
	v_and_b32_e32 v215, 0xffff0000, v63
	v_pk_mul_f32 v[30:31], v[30:31], v[208:209]
	v_pk_mul_f32 v[32:33], v[32:33], v[210:211]
	v_pk_mul_f32 v[212:213], v[64:65], v[212:213] op_sel_hi:[0,1]
	v_pk_mul_f32 v[214:215], v[64:65], v[214:215] op_sel_hi:[0,1]
	v_pk_mul_f32 v[212:213], v[212:213], v[228:229]
	v_pk_mul_f32 v[214:215], v[214:215], v[230:231]
	v_pk_mul_f32 v[30:31], v[30:31], v[212:213]
	v_pk_mul_f32 v[32:33], v[32:33], v[214:215]
	v_cvt_pk_bf16_f32 v30, v30, v31
	v_cvt_pk_bf16_f32 v31, v32, v33
	v_mul_f32_e32 v208, 0xbfb8aa3b, v26
	v_mul_f32_e32 v209, 0xbfb8aa3b, v27
	v_mul_f32_e32 v210, 0xbfb8aa3b, v28
	v_mul_f32_e32 v211, 0xbfb8aa3b, v29
	v_exp_f32_e32 v208, v208
	v_exp_f32_e32 v209, v209
	v_exp_f32_e32 v210, v210
	v_exp_f32_e32 v211, v211
	v_add_f32_e32 v208, 1.0, v208
	v_add_f32_e32 v209, 1.0, v209
	v_add_f32_e32 v210, 1.0, v210
	v_add_f32_e32 v211, 1.0, v211
	v_rcp_f32_e32 v208, v208
	v_rcp_f32_e32 v209, v209
	v_rcp_f32_e32 v210, v210
	v_rcp_f32_e32 v211, v211
	v_lshlrev_b32_e32 v212, 16, v58
	v_and_b32_e32 v213, 0xffff0000, v58
	v_lshlrev_b32_e32 v214, 16, v59
	v_and_b32_e32 v215, 0xffff0000, v59
	v_pk_mul_f32 v[26:27], v[26:27], v[208:209]
	v_pk_mul_f32 v[28:29], v[28:29], v[210:211]
	v_pk_mul_f32 v[212:213], v[64:65], v[212:213] op_sel_hi:[0,1]
	v_pk_mul_f32 v[214:215], v[64:65], v[214:215] op_sel_hi:[0,1]
	v_pk_mul_f32 v[212:213], v[212:213], v[232:233]
	v_pk_mul_f32 v[214:215], v[214:215], v[234:235]
	v_pk_mul_f32 v[26:27], v[26:27], v[212:213]
	v_pk_mul_f32 v[28:29], v[28:29], v[214:215]
	v_cvt_pk_bf16_f32 v26, v26, v27
	v_cvt_pk_bf16_f32 v27, v28, v29
	v_mul_f32_e32 v208, 0xbfb8aa3b, v22
	v_mul_f32_e32 v209, 0xbfb8aa3b, v23
	v_mul_f32_e32 v210, 0xbfb8aa3b, v24
	v_mul_f32_e32 v211, 0xbfb8aa3b, v25
	v_exp_f32_e32 v208, v208
	v_exp_f32_e32 v209, v209
	v_exp_f32_e32 v210, v210
	v_exp_f32_e32 v211, v211
	v_add_f32_e32 v208, 1.0, v208
	v_add_f32_e32 v209, 1.0, v209
	v_add_f32_e32 v210, 1.0, v210
	v_add_f32_e32 v211, 1.0, v211
	v_rcp_f32_e32 v208, v208
	v_rcp_f32_e32 v209, v209
	v_rcp_f32_e32 v210, v210
	v_rcp_f32_e32 v211, v211
	v_lshlrev_b32_e32 v212, 16, v54
	v_and_b32_e32 v213, 0xffff0000, v54
	v_lshlrev_b32_e32 v214, 16, v55
	v_and_b32_e32 v215, 0xffff0000, v55
	v_pk_mul_f32 v[22:23], v[22:23], v[208:209]
	v_pk_mul_f32 v[24:25], v[24:25], v[210:211]
	v_pk_mul_f32 v[212:213], v[64:65], v[212:213] op_sel_hi:[0,1]
	v_pk_mul_f32 v[214:215], v[64:65], v[214:215] op_sel_hi:[0,1]
	v_pk_mul_f32 v[212:213], v[212:213], v[236:237]
	v_pk_mul_f32 v[214:215], v[214:215], v[238:239]
	v_pk_mul_f32 v[22:23], v[22:23], v[212:213]
	v_pk_mul_f32 v[24:25], v[24:25], v[214:215]
	v_cvt_pk_bf16_f32 v22, v22, v23
	v_cvt_pk_bf16_f32 v23, v24, v25
	v_mul_f32_e32 v208, 0xbfb8aa3b, v18
	v_mul_f32_e32 v209, 0xbfb8aa3b, v19
	v_mul_f32_e32 v210, 0xbfb8aa3b, v20
	v_mul_f32_e32 v211, 0xbfb8aa3b, v21
	v_exp_f32_e32 v208, v208
	v_exp_f32_e32 v209, v209
	v_exp_f32_e32 v210, v210
	v_exp_f32_e32 v211, v211
	v_add_f32_e32 v208, 1.0, v208
	v_add_f32_e32 v209, 1.0, v209
	v_add_f32_e32 v210, 1.0, v210
	v_add_f32_e32 v211, 1.0, v211
	v_rcp_f32_e32 v208, v208
	v_rcp_f32_e32 v209, v209
	v_rcp_f32_e32 v210, v210
	v_rcp_f32_e32 v211, v211
	v_lshlrev_b32_e32 v212, 16, v50
	v_and_b32_e32 v213, 0xffff0000, v50
	v_lshlrev_b32_e32 v214, 16, v51
	v_and_b32_e32 v215, 0xffff0000, v51
	v_pk_mul_f32 v[18:19], v[18:19], v[208:209]
	v_pk_mul_f32 v[20:21], v[20:21], v[210:211]
	v_pk_mul_f32 v[212:213], v[64:65], v[212:213] op_sel_hi:[0,1]
	v_pk_mul_f32 v[214:215], v[64:65], v[214:215] op_sel_hi:[0,1]
	v_pk_mul_f32 v[212:213], v[212:213], v[240:241]
	v_pk_mul_f32 v[214:215], v[214:215], v[242:243]
	v_pk_mul_f32 v[18:19], v[18:19], v[212:213]
	v_pk_mul_f32 v[20:21], v[20:21], v[214:215]
	v_cvt_pk_bf16_f32 v18, v18, v19
	v_cvt_pk_bf16_f32 v19, v20, v21
	global_store_dwordx2 v[156:157], v[30:31], off
	global_store_dwordx2 v[156:157], v[26:27], off offset:32
	global_store_dwordx2 v[156:157], v[22:23], off offset:256
	global_store_dwordx2 v[156:157], v[18:19], off offset:288
	s_waitcnt vmcnt(4)
; #define PG8_WAIT_V(n) asm volatile("s_waitcnt vmcnt(" #n ")" ::: "memory")
; #define PG8_BAR __builtin_amdgcn_s_barrier()
; template <class Epi>
; __device__ __forceinline__ void gemm_phase(PG8_LAS unsigned char* lds, const Gemm g, const StaticOrder& S, const Epi& E) {
;     ...
;     E(acc, cur, wr, wc, fr, fq);
;     if (!has_next) break;
; #pragma unroll
;     for (int a = 0; a < 2; ++a)
; #pragma unroll
;       for (int b = 0; b < 2; ++b)
; #pragma unroll
;         for (int m = 0; m < 4; ++m)
; #pragma unroll
;           for (int n = 0; n < 2; ++n) acc[a][b][m][n] = (f32x4){0.f, 0.f, 0.f, 0.f};
;     cur = nxt; cA = nA; cB = nB; ++ui;
;   }
;   PG8_WAIT_V(0);
;   if (wr == 0) PG8_BAR;
;   PG8_BAR;
	v_mul_f32_e32 v208, 0xbfb8aa3b, v14
	v_mul_f32_e32 v209, 0xbfb8aa3b, v15
	v_mul_f32_e32 v210, 0xbfb8aa3b, v16
	v_mul_f32_e32 v211, 0xbfb8aa3b, v17
	v_exp_f32_e32 v208, v208
	v_exp_f32_e32 v209, v209
	v_exp_f32_e32 v210, v210
	v_exp_f32_e32 v211, v211
	v_add_f32_e32 v208, 1.0, v208
	v_add_f32_e32 v209, 1.0, v209
	v_add_f32_e32 v210, 1.0, v210
	v_add_f32_e32 v211, 1.0, v211
	v_rcp_f32_e32 v208, v208
	v_rcp_f32_e32 v209, v209
	v_rcp_f32_e32 v210, v210
	v_rcp_f32_e32 v211, v211
	v_lshlrev_b32_e32 v212, 16, v46
	v_and_b32_e32 v213, 0xffff0000, v46
	v_lshlrev_b32_e32 v214, 16, v47
	v_and_b32_e32 v215, 0xffff0000, v47
	v_pk_mul_f32 v[14:15], v[14:15], v[208:209]
	v_pk_mul_f32 v[16:17], v[16:17], v[210:211]
	v_pk_mul_f32 v[212:213], v[48:49], v[212:213] op_sel_hi:[0,1]
	v_pk_mul_f32 v[214:215], v[48:49], v[214:215] op_sel_hi:[0,1]
	v_pk_mul_f32 v[212:213], v[212:213], v[228:229]
	v_pk_mul_f32 v[214:215], v[214:215], v[230:231]
	v_pk_mul_f32 v[14:15], v[14:15], v[212:213]
	v_pk_mul_f32 v[16:17], v[16:17], v[214:215]
	v_cvt_pk_bf16_f32 v14, v14, v15
	v_cvt_pk_bf16_f32 v15, v16, v17
	v_mul_f32_e32 v208, 0xbfb8aa3b, v10
	v_mul_f32_e32 v209, 0xbfb8aa3b, v11
	v_mul_f32_e32 v210, 0xbfb8aa3b, v12
	v_mul_f32_e32 v211, 0xbfb8aa3b, v13
	v_exp_f32_e32 v208, v208
	v_exp_f32_e32 v209, v209
	v_exp_f32_e32 v210, v210
	v_exp_f32_e32 v211, v211
	v_add_f32_e32 v208, 1.0, v208
	v_add_f32_e32 v209, 1.0, v209
	v_add_f32_e32 v210, 1.0, v210
	v_add_f32_e32 v211, 1.0, v211
	v_rcp_f32_e32 v208, v208
	v_rcp_f32_e32 v209, v209
	v_rcp_f32_e32 v210, v210
	v_rcp_f32_e32 v211, v211
	v_lshlrev_b32_e32 v212, 16, v42
	v_and_b32_e32 v213, 0xffff0000, v42
	v_lshlrev_b32_e32 v214, 16, v43
	v_and_b32_e32 v215, 0xffff0000, v43
	v_pk_mul_f32 v[10:11], v[10:11], v[208:209]
	v_pk_mul_f32 v[12:13], v[12:13], v[210:211]
	v_pk_mul_f32 v[212:213], v[48:49], v[212:213] op_sel_hi:[0,1]
	v_pk_mul_f32 v[214:215], v[48:49], v[214:215] op_sel_hi:[0,1]
	v_pk_mul_f32 v[212:213], v[212:213], v[232:233]
	v_pk_mul_f32 v[214:215], v[214:215], v[234:235]
	v_pk_mul_f32 v[10:11], v[10:11], v[212:213]
	v_pk_mul_f32 v[12:13], v[12:13], v[214:215]
	v_cvt_pk_bf16_f32 v10, v10, v11
	v_cvt_pk_bf16_f32 v11, v12, v13
	v_mul_f32_e32 v208, 0xbfb8aa3b, v6
	v_mul_f32_e32 v209, 0xbfb8aa3b, v7
	v_mul_f32_e32 v210, 0xbfb8aa3b, v8
	v_mul_f32_e32 v211, 0xbfb8aa3b, v9
	v_exp_f32_e32 v208, v208
	v_exp_f32_e32 v209, v209
	v_exp_f32_e32 v210, v210
	v_exp_f32_e32 v211, v211
	v_add_f32_e32 v208, 1.0, v208
	v_add_f32_e32 v209, 1.0, v209
	v_add_f32_e32 v210, 1.0, v210
	v_add_f32_e32 v211, 1.0, v211
	v_rcp_f32_e32 v208, v208
	v_rcp_f32_e32 v209, v209
	v_rcp_f32_e32 v210, v210
	v_rcp_f32_e32 v211, v211
	v_lshlrev_b32_e32 v212, 16, v38
	v_and_b32_e32 v213, 0xffff0000, v38
	v_lshlrev_b32_e32 v214, 16, v39
	v_and_b32_e32 v215, 0xffff0000, v39
	v_pk_mul_f32 v[6:7], v[6:7], v[208:209]
	v_pk_mul_f32 v[8:9], v[8:9], v[210:211]
	v_pk_mul_f32 v[212:213], v[48:49], v[212:213] op_sel_hi:[0,1]
	v_pk_mul_f32 v[214:215], v[48:49], v[214:215] op_sel_hi:[0,1]
	v_pk_mul_f32 v[212:213], v[212:213], v[236:237]
	v_pk_mul_f32 v[214:215], v[214:215], v[238:239]
	v_pk_mul_f32 v[6:7], v[6:7], v[212:213]
	v_pk_mul_f32 v[8:9], v[8:9], v[214:215]
	v_cvt_pk_bf16_f32 v6, v6, v7
	v_cvt_pk_bf16_f32 v7, v8, v9
	v_mul_f32_e32 v208, 0xbfb8aa3b, v2
	v_mul_f32_e32 v209, 0xbfb8aa3b, v3
	v_mul_f32_e32 v210, 0xbfb8aa3b, v4
	v_mul_f32_e32 v211, 0xbfb8aa3b, v5
	v_exp_f32_e32 v208, v208
	v_exp_f32_e32 v209, v209
	v_exp_f32_e32 v210, v210
	v_exp_f32_e32 v211, v211
	v_add_f32_e32 v208, 1.0, v208
	v_add_f32_e32 v209, 1.0, v209
	v_add_f32_e32 v210, 1.0, v210
	v_add_f32_e32 v211, 1.0, v211
	v_rcp_f32_e32 v208, v208
	v_rcp_f32_e32 v209, v209
	v_rcp_f32_e32 v210, v210
	v_rcp_f32_e32 v211, v211
	v_lshlrev_b32_e32 v212, 16, v34
	v_and_b32_e32 v213, 0xffff0000, v34
	v_lshlrev_b32_e32 v214, 16, v35
	v_and_b32_e32 v215, 0xffff0000, v35
	v_pk_mul_f32 v[2:3], v[2:3], v[208:209]
	v_pk_mul_f32 v[4:5], v[4:5], v[210:211]
	v_pk_mul_f32 v[212:213], v[48:49], v[212:213] op_sel_hi:[0,1]
	v_pk_mul_f32 v[214:215], v[48:49], v[214:215] op_sel_hi:[0,1]
	v_pk_mul_f32 v[212:213], v[212:213], v[240:241]
	v_pk_mul_f32 v[214:215], v[214:215], v[242:243]
	v_pk_mul_f32 v[2:3], v[2:3], v[212:213]
	v_pk_mul_f32 v[4:5], v[4:5], v[214:215]
	v_cvt_pk_bf16_f32 v2, v2, v3
	v_cvt_pk_bf16_f32 v3, v4, v5
	global_store_dwordx2 v[158:159], v[14:15], off
	global_store_dwordx2 v[158:159], v[10:11], off offset:32
	global_store_dwordx2 v[158:159], v[6:7], off offset:256
	global_store_dwordx2 v[158:159], v[2:3], off offset:288
	s_mov_b64 s[8:9], s[46:47]
	s_and_b64 vcc, exec, s[40:41]
	s_cbranch_vccz .LBB0_1120
	s_waitcnt vmcnt(0)
	s_cmpk_gt_u32 s19, 0xff
	s_cbranch_scc1 .LBB0_1127
	s_barrier

; __device__ __forceinline__ int ltid() { int t = threadIdx.x; asm volatile("" : "+v"(t)); return t; }
; __device__ __forceinline__ void ph_lru_conv(const P& p, int j) {
;     ...
;   for (int it = xcd_swz(); it < 10400; it += gridDim.x) {
;     int idx = it * 512 + ltid(); int row = idx / 160, cgp = idx % 160, ch = cgp * 8;
;     int b = row / BT_, o = row - b * BT_; int s0 = o < 256 ? 0 : 256, e0 = o < 256 ? 256 : BT_;
;     float acc[8];
; #pragma unroll
;     for (int e = 0; e < 8; e++) acc[e] = cb[ch + e];
; #pragma unroll
;     for (int t = 0; t < 4; t++) { int oo = o + t - 2; if (oo < s0 || oo >= e0) continue;
;       uint4 u = *(const uint4*)(U + (size_t)(row + t - 2) * 1280 + ch); const float* w = cw + t * 1280 + ch;
.LBB0_1569:
	v_mov_b32_e32 v0, v168
	s_mov_b32 s10, 0x66666667
	v_add_u32_e32 v14, s12, v0
	v_mul_hi_i32 v0, v14, s10
	v_lshrrev_b32_e32 v2, 31, v0
	v_ashrrev_i32_e32 v0, 6, v0
	v_add_u32_e32 v0, v0, v2
	s_movk_i32 s10, 0xa0
	v_mul_lo_u32 v2, v0, s10
	v_sub_u32_e32 v2, v14, v2
	v_lshlrev_b32_e32 v0, 1, v0
	v_lshlrev_b32_e32 v10, 3, v2
	v_ashrrev_i32_e32 v11, 31, v10
	v_lshlrev_b64 v[12:13], 2, v[10:11]
	v_lshl_add_u64 v[32:33], s[8:9], 0, v[12:13]
	global_load_dwordx4 v[2:5], v[32:33], off offset:16
	global_load_dwordx4 v[6:9], v[32:33], off
	v_cmp_lt_u32_e32 vcc, 0x40ff, v0
	v_lshl_add_u64 v[14:15], v[10:11], 1, s[2:3]
	v_lshl_add_u64 v[12:13], s[6:7], 0, v[12:13]
	v_cndmask_b32_e32 v16, 0, v185, vcc
	v_sub_u32_e32 v16, v0, v16
	s_movk_i32 s52, 0xa00
	v_cmp_gt_i32_e32 vcc, s65, v16
	s_nop 1
	v_cndmask_b32_e64 v17, v184, 0, vcc
	v_cndmask_b32_e32 v18, v185, v184, vcc
	v_add_u32_e32 v19, -2, v16
	v_cmp_ge_i32_e32 vcc, v19, v17
	v_cmp_lt_i32_e64 s[40:41], v19, v18
	s_nop 0
	s_and_b64 s[42:43], vcc, s[40:41]
	v_add_u32_e32 v19, -1, v16
	v_cmp_ge_i32_e32 vcc, v19, v17
	v_cmp_lt_i32_e64 s[40:41], v19, v18
	s_nop 0
	s_and_b64 s[44:45], vcc, s[40:41]
	v_mov_b32_e32 v19, v16
	v_cmp_ge_i32_e32 vcc, v19, v17
	v_cmp_lt_i32_e64 s[40:41], v19, v18
	s_nop 0
	s_and_b64 s[46:47], vcc, s[40:41]
	v_add_u32_e32 v19, 1, v16
	v_cmp_ge_i32_e32 vcc, v19, v17
	v_cmp_lt_i32_e64 s[40:41], v19, v18
	s_nop 0
	s_and_b64 s[48:49], vcc, s[40:41]
	v_add_u32_e32 v19, 2, v16
	v_cmp_ge_i32_e32 vcc, v19, v17
	v_cmp_lt_i32_e64 s[40:41], v19, v18
	s_nop 0
	s_and_b64 s[50:51], vcc, s[40:41]
	s_and_saveexec_b64 s[10:11], s[42:43]
	v_add_u32_e32 v19, -2, v0
	v_mad_i64_i32 v[20:21], s[18:19], v19, s52, v[14:15]
	global_load_dwordx4 v[36:39], v[20:21], off
	s_or_b64 exec, exec, s[10:11]
	s_and_saveexec_b64 s[10:11], s[44:45]
	v_add_u32_e32 v19, -1, v0
	v_mad_i64_i32 v[20:21], s[18:19], v19, s52, v[14:15]
	global_load_dwordx4 v[40:43], v[20:21], off
	s_or_b64 exec, exec, s[10:11]
	s_and_saveexec_b64 s[10:11], s[46:47]
	v_mov_b32_e32 v19, v0
	v_mad_i64_i32 v[20:21], s[18:19], v19, s52, v[14:15]
	global_load_dwordx4 v[44:47], v[20:21], off
	s_or_b64 exec, exec, s[10:11]
	s_and_saveexec_b64 s[10:11], s[48:49]
	v_add_u32_e32 v19, 1, v0
	v_mad_i64_i32 v[20:21], s[18:19], v19, s52, v[14:15]
	global_load_dwordx4 v[48:51], v[20:21], off
	s_or_b64 exec, exec, s[10:11]
	s_and_saveexec_b64 s[10:11], s[50:51]
	v_add_u32_e32 v19, 2, v0
	v_mad_i64_i32 v[20:21], s[18:19], v19, s52, v[14:15]
	global_load_dwordx4 v[52:55], v[20:21], off
	s_or_b64 exec, exec, s[10:11]
	global_load_dwordx4 v[56:59], v[12:13], off
	global_load_dwordx4 v[60:63], v[12:13], off offset:16
	v_add_co_u32_e32 v22, vcc, 0x1400, v12
	s_nop 1
	v_addc_co_u32_e32 v23, vcc, 0, v13, vcc
	global_load_dwordx4 v[64:67], v[22:23], off
	global_load_dwordx4 v[68:71], v[22:23], off offset:16
	v_add_co_u32_e32 v22, vcc, 0x2800, v12
	s_nop 1
	v_addc_co_u32_e32 v23, vcc, 0, v13, vcc
	global_load_dwordx4 v[72:75], v[22:23], off
	global_load_dwordx4 v[76:79], v[22:23], off offset:16
	v_add_co_u32_e32 v22, vcc, 0x3c00, v12
	s_nop 1
	v_addc_co_u32_e32 v23, vcc, 0, v13, vcc
	global_load_dwordx4 v[80:83], v[22:23], off
	global_load_dwordx4 v[84:87], v[22:23], off offset:16
	s_waitcnt vmcnt(0)
; __device__ __forceinline__ unsigned pk2(float a, float b) { return cvtpk(a, b); }
; __device__ __forceinline__ float blo(unsigned u) { return __uint_as_float(u << 16); }
; __device__ __forceinline__ float bhi(unsigned u) { return __uint_as_float(u & 0xffff0000u); }
; __device__ __forceinline__ void ph_lru_conv(const P& p, int j) {
;     ...
;     for (int t = 0; t < 4; t++) { int oo = o + t - 2; if (oo < s0 || oo >= e0) continue;
;       uint4 u = *(const uint4*)(U + (size_t)(row + t - 2) * 1280 + ch); const float* w = cw + t * 1280 + ch;
;       acc[0] += w[0] * blo(u.x); acc[1] += w[1] * bhi(u.x); acc[2] += w[2] * blo(u.y); acc[3] += w[3] * bhi(u.y);
;       acc[4] += w[4] * blo(u.z); acc[5] += w[5] * bhi(u.z); acc[6] += w[6] * blo(u.w); acc[7] += w[7] * bhi(u.w); }
;     *(uint4*)(UC + (size_t)row * 1280 + ch) = uint4{pk2(acc[0], acc[1]), pk2(acc[2], acc[3]), pk2(acc[4], acc[5]), pk2(acc[6], acc[7])};
	v_mov_b32_e32 v96, v6
	v_mov_b32_e32 v97, v7
	v_mov_b32_e32 v98, v8
	v_mov_b32_e32 v99, v9
	v_mov_b32_e32 v100, v2
	v_mov_b32_e32 v101, v3
	v_mov_b32_e32 v102, v4
	v_mov_b32_e32 v103, v5
	s_and_saveexec_b64 s[10:11], s[42:43]
	v_lshlrev_b32_e32 v24, 16, v36
	v_and_b32_e32 v25, 0xffff0000, v36
	v_lshlrev_b32_e32 v26, 16, v37
	v_and_b32_e32 v27, 0xffff0000, v37
	v_lshlrev_b32_e32 v28, 16, v38
	v_and_b32_e32 v29, 0xffff0000, v38
	v_lshlrev_b32_e32 v30, 16, v39
	v_and_b32_e32 v31, 0xffff0000, v39
	v_pk_fma_f32 v[6:7], v[56:57], v[24:25], v[6:7]
	v_pk_fma_f32 v[8:9], v[58:59], v[26:27], v[8:9]
	v_pk_fma_f32 v[2:3], v[60:61], v[28:29], v[2:3]
	v_pk_fma_f32 v[4:5], v[62:63], v[30:31], v[4:5]
	s_or_b64 exec, exec, s[10:11]
	s_and_saveexec_b64 s[10:11], s[44:45]
	v_lshlrev_b32_e32 v24, 16, v40
	v_and_b32_e32 v25, 0xffff0000, v40
	v_lshlrev_b32_e32 v26, 16, v41
	v_and_b32_e32 v27, 0xffff0000, v41
	v_lshlrev_b32_e32 v28, 16, v42
	v_and_b32_e32 v29, 0xffff0000, v42
	v_lshlrev_b32_e32 v30, 16, v43
	v_and_b32_e32 v31, 0xffff0000, v43
	v_pk_fma_f32 v[6:7], v[64:65], v[24:25], v[6:7]
	v_pk_fma_f32 v[8:9], v[66:67], v[26:27], v[8:9]
	v_pk_fma_f32 v[2:3], v[68:69], v[28:29], v[2:3]
	v_pk_fma_f32 v[4:5], v[70:71], v[30:31], v[4:5]
	v_pk_fma_f32 v[96:97], v[56:57], v[24:25], v[96:97]
	v_pk_fma_f32 v[98:99], v[58:59], v[26:27], v[98:99]
	v_pk_fma_f32 v[100:101], v[60:61], v[28:29], v[100:101]
	v_pk_fma_f32 v[102:103], v[62:63], v[30:31], v[102:103]
	s_or_b64 exec, exec, s[10:11]
	s_and_saveexec_b64 s[10:11], s[46:47]
	v_lshlrev_b32_e32 v24, 16, v44
	v_and_b32_e32 v25, 0xffff0000, v44
	v_lshlrev_b32_e32 v26, 16, v45
	v_and_b32_e32 v27, 0xffff0000, v45
	v_lshlrev_b32_e32 v28, 16, v46
	v_and_b32_e32 v29, 0xffff0000, v46
	v_lshlrev_b32_e32 v30, 16, v47
	v_and_b32_e32 v31, 0xffff0000, v47
	v_pk_fma_f32 v[6:7], v[72:73], v[24:25], v[6:7]
	v_pk_fma_f32 v[8:9], v[74:75], v[26:27], v[8:9]
	v_pk_fma_f32 v[2:3], v[76:77], v[28:29], v[2:3]
	v_pk_fma_f32 v[4:5], v[78:79], v[30:31], v[4:5]
	v_pk_fma_f32 v[96:97], v[64:65], v[24:25], v[96:97]
	v_pk_fma_f32 v[98:99], v[66:67], v[26:27], v[98:99]
	v_pk_fma_f32 v[100:101], v[68:69], v[28:29], v[100:101]
	v_pk_fma_f32 v[102:103], v[70:71], v[30:31], v[102:103]
	s_or_b64 exec, exec, s[10:11]
	s_and_saveexec_b64 s[10:11], s[48:49]
	v_lshlrev_b32_e32 v24, 16, v48
	v_and_b32_e32 v25, 0xffff0000, v48
	v_lshlrev_b32_e32 v26, 16, v49
	v_and_b32_e32 v27, 0xffff0000, v49
	v_lshlrev_b32_e32 v28, 16, v50
	v_and_b32_e32 v29, 0xffff0000, v50
	v_lshlrev_b32_e32 v30, 16, v51
	v_and_b32_e32 v31, 0xffff0000, v51
	v_pk_fma_f32 v[6:7], v[80:81], v[24:25], v[6:7]
	v_pk_fma_f32 v[8:9], v[82:83], v[26:27], v[8:9]
	v_pk_fma_f32 v[2:3], v[84:85], v[28:29], v[2:3]
	v_pk_fma_f32 v[4:5], v[86:87], v[30:31], v[4:5]
	v_pk_fma_f32 v[96:97], v[72:73], v[24:25], v[96:97]
	v_pk_fma_f32 v[98:99], v[74:75], v[26:27], v[98:99]
	v_pk_fma_f32 v[100:101], v[76:77], v[28:29], v[100:101]
	v_pk_fma_f32 v[102:103], v[78:79], v[30:31], v[102:103]
	s_or_b64 exec, exec, s[10:11]
	s_and_saveexec_b64 s[10:11], s[50:51]
	v_lshlrev_b32_e32 v24, 16, v52
	v_and_b32_e32 v25, 0xffff0000, v52
	v_lshlrev_b32_e32 v26, 16, v53
	v_and_b32_e32 v27, 0xffff0000, v53
	v_lshlrev_b32_e32 v28, 16, v54
	v_and_b32_e32 v29, 0xffff0000, v54
	v_lshlrev_b32_e32 v30, 16, v55
	v_and_b32_e32 v31, 0xffff0000, v55
	v_pk_fma_f32 v[96:97], v[80:81], v[24:25], v[96:97]
	v_pk_fma_f32 v[98:99], v[82:83], v[26:27], v[98:99]
	v_pk_fma_f32 v[100:101], v[84:85], v[28:29], v[100:101]
	v_pk_fma_f32 v[102:103], v[86:87], v[30:31], v[102:103]
	s_or_b64 exec, exec, s[10:11]
	v_readlane_b32 s10, v251, 49
	v_readlane_b32 s11, v251, 50
	v_cvt_pk_bf16_f32 v6, v6, v7
	v_cvt_pk_bf16_f32 v7, v8, v9
	v_cvt_pk_bf16_f32 v8, v2, v3
	v_cvt_pk_bf16_f32 v9, v4, v5
	v_cvt_pk_bf16_f32 v96, v96, v97
	v_cvt_pk_bf16_f32 v97, v98, v99
	v_cvt_pk_bf16_f32 v98, v100, v101
	v_cvt_pk_bf16_f32 v99, v102, v103
	v_mov_b64_e32 v[2:3], s[10:11]
	v_mad_i64_i32 v[2:3], s[10:11], v0, s52, v[2:3]
	v_readlane_b32 s10, v253, 18
	s_add_i32 s13, s13, s96
	s_add_i32 s12, s12, s10
	v_lshl_add_u64 v[2:3], v[10:11], 1, v[2:3]
	s_cmpk_gt_i32 s13, 0x144f
	global_store_dwordx4 v[2:3], v[6:9], off
	global_store_dwordx4 v[2:3], v[96:99], off offset:2560
	s_cbranch_scc0 .LBB0_1569
